# removed per-segment s_setprio toggles from the six GEMM K-loops (priority showed no effect either way; fewer scalar issue slots inside the MFMA clusters)
# speedup vs baseline: 1.0101x; 1.0101x over previous
; #define PG8_STAGE(bufoff, gbase, voff) do { _Pragma("unroll") for (int _i = 0; _i < 2; ++_i) \
;         __builtin_amdgcn_global_load_lds((const unsigned*)((const char*)(gbase) + (voff)[_i]), (LAS unsigned*)(lds + (bufoff) + ldsw + _i * 8192), 16, 0, 0); } while (0)
; #define PG8_LDA(dst, b, h) do { _Pragma("unroll") for (int m = 0; m < 4; ++m) _Pragma("unroll") for (int k = 0; k < 2; ++k) dst[m][k] = *(const LAS bf16x8*)(lds + PG8_SA(b, h) + aoff + m * 2048 + k * 1024); } while (0)
; #define PG8_LDB(dst, b, h) do { _Pragma("unroll") for (int n = 0; n < 2; ++n) _Pragma("unroll") for (int k = 0; k < 2; ++k) dst[n][k] = *(const LAS bf16x8*)(lds + PG8_SB(b, h) + boff + n * 2048 + k * 1024); } while (0)
; #define PG8_MMA(ai, bj, At, Bt) do { __builtin_amdgcn_s_setprio(1); _Pragma("unroll") for (int m = 0; m < 4; ++m) _Pragma("unroll") for (int n = 0; n < 2; ++n) _Pragma("unroll") for (int k = 0; k < 2; ++k) \
;         acc[ai][bj][m][n] = __builtin_amdgcn_mfma_f32_16x16x32_bf16(Bt[n][k], At[m][k], acc[ai][bj][m][n], 0, 0, 0); __builtin_amdgcn_s_setprio(0); } while (0)
; #define PG8_WAIT_V(n) asm volatile("s_waitcnt vmcnt(" #n ")" ::: "memory")
; #define PG8_WAIT_L(n) asm volatile("s_waitcnt lgkmcnt(" #n ")" ::: "memory")
; #define PG8_BAR __builtin_amdgcn_s_barrier()
; #define PG8_SCHED __builtin_amdgcn_sched_barrier(0)
; template <class Epi>
; __device__ __forceinline__ void gemm_phase(LAS unsigned char* lds, const Gemm g, const StaticOrder& S, const Epi& E) {
;     ...
;             PG8_LDB(B0, 0, 0); PG8_LDB(B1, 0, 1); PG8_SCHED; PG8_LDA(At, 0, 0); PG8_STAGE(PG8_SA(1, 1), a1 + hstep, voffA);
;             PG8_WAIT_V(8); PG8_WAIT_L(0); PG8_BAR; PG8_MMA(0, 0, At, B0); PG8_MMA(0, 1, At, B1); PG8_BAR; PG8_SCHED;
;             PG8_LDA(At, 0, 1); PG8_STAGE(PG8_SB(0, 0), b2, voffB); PG8_STAGE(PG8_SB(0, 1), b2 + hstep, voffB); PG8_STAGE(PG8_SA(0, 0), a2, voffA);
;             PG8_WAIT_V(8); PG8_WAIT_L(0); PG8_BAR; PG8_MMA(1, 0, At, B0); PG8_MMA(1, 1, At, B1); PG8_BAR; PG8_SCHED;
.LBB0_249:
	s_or_b64 exec, exec, s[12:13]
	v_or_b32_e32 v149, 0x10000, v153
	v_add_u32_e32 v150, 0x10400, v153
	ds_read_b128 v[170:173], v149
	ds_read_b128 v[174:177], v150
	v_add_u32_e32 v149, 0x10800, v153
	v_add_u32_e32 v150, 0x10c00, v153
	ds_read_b128 v[178:181], v149
	ds_read_b128 v[182:185], v150
	v_or_b32_e32 v149, 0x14000, v153
	v_add_u32_e32 v150, 0x14400, v153
	ds_read_b128 v[186:189], v149
	ds_read_b128 v[190:193], v150
	v_add_u32_e32 v149, 0x14800, v153
	v_add_u32_e32 v150, 0x14c00, v153
	ds_read_b128 v[194:197], v149
	ds_read_b128 v[198:201], v150
	s_add_i32 s56, s56, 2
	s_add_u32 s12, s2, 0x80
	s_addc_u32 s13, s3, 0
	s_and_b64 s[10:11], s[10:11], exec
	s_cselect_b32 s11, s13, s45
	s_cselect_b32 s10, s12, s44
	s_cselect_b32 s13, s49, s47
	s_cselect_b32 s12, s48, s46
	s_mov_b32 m0, s58
	v_lshl_add_u64 v[150:151], s[2:3], 0, v[142:143]
	ds_read_b128 v[202:205], v152
	ds_read_b128 v[206:209], v152 offset:1024
	ds_read_b128 v[226:229], v152 offset:2048
	ds_read_b128 v[230:233], v152 offset:3072
	ds_read_b128 v[234:237], v152 offset:4096
	ds_read_b128 v[238:241], v152 offset:5120
	ds_read_b128 v[242:245], v152 offset:6144
	ds_read_b128 v[246:249], v152 offset:7168
	global_load_lds_dwordx4 v[150:151], off
	v_lshl_add_u64 v[150:151], s[2:3], 0, v[144:145]
	s_mov_b32 m0, s19
	s_nop 0
	global_load_lds_dwordx4 v[150:151], off
	s_waitcnt vmcnt(8)
	s_waitcnt lgkmcnt(0)
	s_barrier
	s_waitcnt lgkmcnt(0)
	v_mfma_f32_16x16x32_bf16 v[124:127], v[170:173], v[202:205], v[124:127]
	v_mfma_f32_16x16x32_bf16 v[120:123], v[178:181], v[202:205], v[120:123]
	v_mfma_f32_16x16x32_bf16 v[108:111], v[170:173], v[226:229], v[108:111]
	v_mfma_f32_16x16x32_bf16 v[104:107], v[178:181], v[226:229], v[104:107]
	v_mfma_f32_16x16x32_bf16 v[92:95], v[170:173], v[234:237], v[92:95]
	v_mfma_f32_16x16x32_bf16 v[88:91], v[178:181], v[234:237], v[88:91]
	v_mfma_f32_16x16x32_bf16 v[76:79], v[170:173], v[242:245], v[76:79]
	v_mfma_f32_16x16x32_bf16 v[72:75], v[178:181], v[242:245], v[72:75]
	v_mfma_f32_16x16x32_bf16 v[124:127], v[174:177], v[206:209], v[124:127]
	v_mfma_f32_16x16x32_bf16 v[120:123], v[182:185], v[206:209], v[120:123]
	v_mfma_f32_16x16x32_bf16 v[108:111], v[174:177], v[230:233], v[108:111]
	v_mfma_f32_16x16x32_bf16 v[104:107], v[182:185], v[230:233], v[104:107]
	v_mfma_f32_16x16x32_bf16 v[92:95], v[174:177], v[238:241], v[92:95]
	v_mfma_f32_16x16x32_bf16 v[88:91], v[182:185], v[238:241], v[88:91]
	v_mfma_f32_16x16x32_bf16 v[76:79], v[174:177], v[246:249], v[76:79]
	v_mfma_f32_16x16x32_bf16 v[72:75], v[182:185], v[246:249], v[72:75]
	v_mfma_f32_16x16x32_bf16 v[116:119], v[186:189], v[202:205], v[116:119]
	v_mfma_f32_16x16x32_bf16 v[112:115], v[194:197], v[202:205], v[112:115]
	v_mfma_f32_16x16x32_bf16 v[100:103], v[186:189], v[226:229], v[100:103]
	v_mfma_f32_16x16x32_bf16 v[96:99], v[194:197], v[226:229], v[96:99]
	v_mfma_f32_16x16x32_bf16 v[84:87], v[186:189], v[234:237], v[84:87]
	v_mfma_f32_16x16x32_bf16 v[80:83], v[194:197], v[234:237], v[80:83]
	v_mfma_f32_16x16x32_bf16 v[68:71], v[186:189], v[242:245], v[68:71]
	v_mfma_f32_16x16x32_bf16 v[64:67], v[194:197], v[242:245], v[64:67]
	v_mfma_f32_16x16x32_bf16 v[116:119], v[190:193], v[206:209], v[116:119]
	v_mfma_f32_16x16x32_bf16 v[112:115], v[198:201], v[206:209], v[112:115]
	v_mfma_f32_16x16x32_bf16 v[100:103], v[190:193], v[230:233], v[100:103]
	v_mfma_f32_16x16x32_bf16 v[96:99], v[198:201], v[230:233], v[96:99]
	v_mfma_f32_16x16x32_bf16 v[84:87], v[190:193], v[238:241], v[84:87]
	v_mfma_f32_16x16x32_bf16 v[80:83], v[198:201], v[238:241], v[80:83]
	v_mfma_f32_16x16x32_bf16 v[68:71], v[190:193], v[246:249], v[68:71]
	v_mfma_f32_16x16x32_bf16 v[64:67], v[198:201], v[246:249], v[64:67]
	s_barrier
	s_mov_b32 m0, s59
	v_lshl_add_u64 v[150:151], s[12:13], 0, v[130:131]
	v_lshl_add_u64 v[210:211], s[12:13], 0, v[134:135]
	s_add_u32 s12, s12, s30
	ds_read_b128 v[202:205], v152 offset:16384
	ds_read_b128 v[206:209], v152 offset:17408
	ds_read_b128 v[226:229], v152 offset:18432
	ds_read_b128 v[230:233], v152 offset:19456
	ds_read_b128 v[234:237], v152 offset:20480
	ds_read_b128 v[238:241], v152 offset:21504
	ds_read_b128 v[242:245], v152 offset:22528
	ds_read_b128 v[246:249], v152 offset:23552
	global_load_lds_dwordx4 v[150:151], off
	s_mov_b32 m0, s60
	s_addc_u32 s13, s13, s31
	global_load_lds_dwordx4 v[210:211], off
	v_lshl_add_u64 v[250:251], s[12:13], 0, v[130:131]
	s_mov_b32 m0, s61
	v_lshl_add_u64 v[252:253], s[12:13], 0, v[134:135]
	global_load_lds_dwordx4 v[250:251], off
	s_mov_b32 m0, s62
	v_lshl_add_u64 v[218:219], s[10:11], 0, v[128:129]
	global_load_lds_dwordx4 v[252:253], off
	s_mov_b32 m0, s18
	v_lshl_add_u64 v[216:217], s[10:11], 0, v[132:133]
	global_load_lds_dwordx4 v[218:219], off
	s_mov_b32 m0, s63
	s_nop 0
	global_load_lds_dwordx4 v[216:217], off
	s_waitcnt vmcnt(8)
	s_waitcnt lgkmcnt(0)
	s_barrier
; #define PG8_STAGE(bufoff, gbase, voff) do { _Pragma("unroll") for (int _i = 0; _i < 2; ++_i) \
;         __builtin_amdgcn_global_load_lds((const unsigned*)((const char*)(gbase) + (voff)[_i]), (LAS unsigned*)(lds + (bufoff) + ldsw + _i * 8192), 16, 0, 0); } while (0)
; #define PG8_LDA(dst, b, h) do { _Pragma("unroll") for (int m = 0; m < 4; ++m) _Pragma("unroll") for (int k = 0; k < 2; ++k) dst[m][k] = *(const LAS bf16x8*)(lds + PG8_SA(b, h) + aoff + m * 2048 + k * 1024); } while (0)
; #define PG8_LDB(dst, b, h) do { _Pragma("unroll") for (int n = 0; n < 2; ++n) _Pragma("unroll") for (int k = 0; k < 2; ++k) dst[n][k] = *(const LAS bf16x8*)(lds + PG8_SB(b, h) + boff + n * 2048 + k * 1024); } while (0)
; #define PG8_MMA(ai, bj, At, Bt) do { __builtin_amdgcn_s_setprio(1); _Pragma("unroll") for (int m = 0; m < 4; ++m) _Pragma("unroll") for (int n = 0; n < 2; ++n) _Pragma("unroll") for (int k = 0; k < 2; ++k) \
;         acc[ai][bj][m][n] = __builtin_amdgcn_mfma_f32_16x16x32_bf16(Bt[n][k], At[m][k], acc[ai][bj][m][n], 0, 0, 0); __builtin_amdgcn_s_setprio(0); } while (0)
; #define PG8_WAIT_V(n) asm volatile("s_waitcnt vmcnt(" #n ")" ::: "memory")
; #define PG8_WAIT_L(n) asm volatile("s_waitcnt lgkmcnt(" #n ")" ::: "memory")
; #define PG8_BAR __builtin_amdgcn_s_barrier()
; #define PG8_SCHED __builtin_amdgcn_sched_barrier(0)
; template <class Epi>
; __device__ __forceinline__ void gemm_phase(LAS unsigned char* lds, const Gemm g, const StaticOrder& S, const Epi& E) {
;     ...
;             PG8_WAIT_V(8); PG8_WAIT_L(0); PG8_BAR; PG8_MMA(1, 0, At, B0); PG8_MMA(1, 1, At, B1); PG8_BAR; PG8_SCHED;
;             PG8_LDB(B0, 1, 0); PG8_LDB(B1, 1, 1); PG8_SCHED; PG8_LDA(At, 1, 0); PG8_STAGE(PG8_SA(0, 1), a2 + hstep, voffA);
;             PG8_WAIT_V(8); PG8_WAIT_L(0); PG8_BAR; PG8_MMA(0, 0, At, B0); PG8_MMA(0, 1, At, B1); PG8_BAR; PG8_SCHED;
	s_waitcnt lgkmcnt(0)
	v_mfma_f32_16x16x32_bf16 v[60:63], v[170:173], v[202:205], v[60:63]
	v_mfma_f32_16x16x32_bf16 v[56:59], v[178:181], v[202:205], v[56:59]
	v_mfma_f32_16x16x32_bf16 v[44:47], v[170:173], v[226:229], v[44:47]
	v_mfma_f32_16x16x32_bf16 v[40:43], v[178:181], v[226:229], v[40:43]
	v_mfma_f32_16x16x32_bf16 v[28:31], v[170:173], v[234:237], v[28:31]
	v_mfma_f32_16x16x32_bf16 v[24:27], v[178:181], v[234:237], v[24:27]
	v_mfma_f32_16x16x32_bf16 v[12:15], v[170:173], v[242:245], v[12:15]
	v_mfma_f32_16x16x32_bf16 v[8:11], v[178:181], v[242:245], v[8:11]
	v_mfma_f32_16x16x32_bf16 v[60:63], v[174:177], v[206:209], v[60:63]
	v_mfma_f32_16x16x32_bf16 v[56:59], v[182:185], v[206:209], v[56:59]
	v_mfma_f32_16x16x32_bf16 v[44:47], v[174:177], v[230:233], v[44:47]
	v_mfma_f32_16x16x32_bf16 v[40:43], v[182:185], v[230:233], v[40:43]
	v_mfma_f32_16x16x32_bf16 v[28:31], v[174:177], v[238:241], v[28:31]
	v_mfma_f32_16x16x32_bf16 v[24:27], v[182:185], v[238:241], v[24:27]
	v_mfma_f32_16x16x32_bf16 v[12:15], v[174:177], v[246:249], v[12:15]
	v_mfma_f32_16x16x32_bf16 v[8:11], v[182:185], v[246:249], v[8:11]
	v_mfma_f32_16x16x32_bf16 v[52:55], v[186:189], v[202:205], v[52:55]
	v_mfma_f32_16x16x32_bf16 v[48:51], v[194:197], v[202:205], v[48:51]
	v_mfma_f32_16x16x32_bf16 v[36:39], v[186:189], v[226:229], v[36:39]
	v_mfma_f32_16x16x32_bf16 v[32:35], v[194:197], v[226:229], v[32:35]
	v_mfma_f32_16x16x32_bf16 v[20:23], v[186:189], v[234:237], v[20:23]
	v_mfma_f32_16x16x32_bf16 v[16:19], v[194:197], v[234:237], v[16:19]
	v_mfma_f32_16x16x32_bf16 v[4:7], v[186:189], v[242:245], v[4:7]
	v_mfma_f32_16x16x32_bf16 v[0:3], v[194:197], v[242:245], v[0:3]
	v_mfma_f32_16x16x32_bf16 v[52:55], v[190:193], v[206:209], v[52:55]
	v_mfma_f32_16x16x32_bf16 v[48:51], v[198:201], v[206:209], v[48:51]
	v_mfma_f32_16x16x32_bf16 v[36:39], v[190:193], v[230:233], v[36:39]
	v_mfma_f32_16x16x32_bf16 v[32:35], v[198:201], v[230:233], v[32:35]
	v_mfma_f32_16x16x32_bf16 v[20:23], v[190:193], v[238:241], v[20:23]
	v_mfma_f32_16x16x32_bf16 v[16:19], v[198:201], v[238:241], v[16:19]
	v_mfma_f32_16x16x32_bf16 v[4:7], v[190:193], v[246:249], v[4:7]
	v_mfma_f32_16x16x32_bf16 v[0:3], v[198:201], v[246:249], v[0:3]
	s_barrier
	v_or_b32_e32 v149, 0x18000, v153
	v_add_u32_e32 v156, 0x18400, v153
	ds_read_b128 v[170:173], v149
	ds_read_b128 v[174:177], v156
	v_add_u32_e32 v149, 0x18800, v153
	v_add_u32_e32 v156, 0x18c00, v153
	ds_read_b128 v[178:181], v149
	ds_read_b128 v[182:185], v156
	v_or_b32_e32 v149, 0x1c000, v153
	v_add_u32_e32 v156, 0x1c400, v153
	ds_read_b128 v[186:189], v149
	ds_read_b128 v[190:193], v156
	v_add_u32_e32 v149, 0x1c800, v153
	v_add_u32_e32 v156, 0x1cc00, v153
	ds_read_b128 v[194:197], v149
	ds_read_b128 v[198:201], v156
	s_add_u32 s10, s10, s30
	s_addc_u32 s11, s11, s31
	s_mov_b32 m0, s64
	v_lshl_add_u64 v[220:221], s[10:11], 0, v[128:129]
	ds_read_b128 v[202:205], v152 offset:32768
	ds_read_b128 v[206:209], v152 offset:33792
	ds_read_b128 v[226:229], v152 offset:34816
	ds_read_b128 v[230:233], v152 offset:35840
	ds_read_b128 v[234:237], v152 offset:36864
	ds_read_b128 v[238:241], v152 offset:37888
	ds_read_b128 v[242:245], v152 offset:38912
	ds_read_b128 v[246:249], v152 offset:39936
	global_load_lds_dwordx4 v[220:221], off
	v_lshl_add_u64 v[220:221], s[10:11], 0, v[132:133]
	s_mov_b32 m0, s65
	s_nop 0
	global_load_lds_dwordx4 v[220:221], off
	s_waitcnt vmcnt(8)
	s_waitcnt lgkmcnt(0)
	s_barrier
	s_waitcnt lgkmcnt(0)
	v_mfma_f32_16x16x32_bf16 v[124:127], v[170:173], v[202:205], v[124:127]
	v_mfma_f32_16x16x32_bf16 v[120:123], v[178:181], v[202:205], v[120:123]
	v_mfma_f32_16x16x32_bf16 v[108:111], v[170:173], v[226:229], v[108:111]
	v_mfma_f32_16x16x32_bf16 v[104:107], v[178:181], v[226:229], v[104:107]
	v_mfma_f32_16x16x32_bf16 v[92:95], v[170:173], v[234:237], v[92:95]
	v_mfma_f32_16x16x32_bf16 v[88:91], v[178:181], v[234:237], v[88:91]
	v_mfma_f32_16x16x32_bf16 v[76:79], v[170:173], v[242:245], v[76:79]
	v_mfma_f32_16x16x32_bf16 v[72:75], v[178:181], v[242:245], v[72:75]
	v_mfma_f32_16x16x32_bf16 v[124:127], v[174:177], v[206:209], v[124:127]
	v_mfma_f32_16x16x32_bf16 v[120:123], v[182:185], v[206:209], v[120:123]
	v_mfma_f32_16x16x32_bf16 v[108:111], v[174:177], v[230:233], v[108:111]
	v_mfma_f32_16x16x32_bf16 v[104:107], v[182:185], v[230:233], v[104:107]
	v_mfma_f32_16x16x32_bf16 v[92:95], v[174:177], v[238:241], v[92:95]
	v_mfma_f32_16x16x32_bf16 v[88:91], v[182:185], v[238:241], v[88:91]
	v_mfma_f32_16x16x32_bf16 v[76:79], v[174:177], v[246:249], v[76:79]
	v_mfma_f32_16x16x32_bf16 v[72:75], v[182:185], v[246:249], v[72:75]
	v_mfma_f32_16x16x32_bf16 v[116:119], v[186:189], v[202:205], v[116:119]
	v_mfma_f32_16x16x32_bf16 v[112:115], v[194:197], v[202:205], v[112:115]
	v_mfma_f32_16x16x32_bf16 v[100:103], v[186:189], v[226:229], v[100:103]
	v_mfma_f32_16x16x32_bf16 v[96:99], v[194:197], v[226:229], v[96:99]
	v_mfma_f32_16x16x32_bf16 v[84:87], v[186:189], v[234:237], v[84:87]
	v_mfma_f32_16x16x32_bf16 v[80:83], v[194:197], v[234:237], v[80:83]
	v_mfma_f32_16x16x32_bf16 v[68:71], v[186:189], v[242:245], v[68:71]
	v_mfma_f32_16x16x32_bf16 v[64:67], v[194:197], v[242:245], v[64:67]
	v_mfma_f32_16x16x32_bf16 v[116:119], v[190:193], v[206:209], v[116:119]
	v_mfma_f32_16x16x32_bf16 v[112:115], v[198:201], v[206:209], v[112:115]
	v_mfma_f32_16x16x32_bf16 v[100:103], v[190:193], v[230:233], v[100:103]
	v_mfma_f32_16x16x32_bf16 v[96:99], v[198:201], v[230:233], v[96:99]
	v_mfma_f32_16x16x32_bf16 v[84:87], v[190:193], v[238:241], v[84:87]
	v_mfma_f32_16x16x32_bf16 v[80:83], v[198:201], v[238:241], v[80:83]
	v_mfma_f32_16x16x32_bf16 v[68:71], v[190:193], v[246:249], v[68:71]
	v_mfma_f32_16x16x32_bf16 v[64:67], v[198:201], v[246:249], v[64:67]
	s_barrier
; #define PG8_STAGE(bufoff, gbase, voff) do { _Pragma("unroll") for (int _i = 0; _i < 2; ++_i) \
;         __builtin_amdgcn_global_load_lds((const unsigned*)((const char*)(gbase) + (voff)[_i]), (LAS unsigned*)(lds + (bufoff) + ldsw + _i * 8192), 16, 0, 0); } while (0)
; #define PG8_LDA(dst, b, h) do { _Pragma("unroll") for (int m = 0; m < 4; ++m) _Pragma("unroll") for (int k = 0; k < 2; ++k) dst[m][k] = *(const LAS bf16x8*)(lds + PG8_SA(b, h) + aoff + m * 2048 + k * 1024); } while (0)
; #define PG8_MMA(ai, bj, At, Bt) do { __builtin_amdgcn_s_setprio(1); _Pragma("unroll") for (int m = 0; m < 4; ++m) _Pragma("unroll") for (int n = 0; n < 2; ++n) _Pragma("unroll") for (int k = 0; k < 2; ++k) \
;         acc[ai][bj][m][n] = __builtin_amdgcn_mfma_f32_16x16x32_bf16(Bt[n][k], At[m][k], acc[ai][bj][m][n], 0, 0, 0); __builtin_amdgcn_s_setprio(0); } while (0)
; #define PG8_WAIT_V(n) asm volatile("s_waitcnt vmcnt(" #n ")" ::: "memory")
; #define PG8_WAIT_L(n) asm volatile("s_waitcnt lgkmcnt(" #n ")" ::: "memory")
; #define PG8_BAR __builtin_amdgcn_s_barrier()
; #define PG8_SCHED __builtin_amdgcn_sched_barrier(0)
; template <class Epi>
; __device__ __forceinline__ void gemm_phase(LAS unsigned char* lds, const Gemm g, const StaticOrder& S, const Epi& E) {
;     ...
;             PG8_LDA(At, 1, 1); PG8_STAGE(PG8_SB(1, 0), b3, voffB); PG8_STAGE(PG8_SB(1, 1), b3 + hstep, voffB); PG8_STAGE(PG8_SA(1, 0), a3, voffA);
;             PG8_WAIT_V(8); PG8_WAIT_L(0); PG8_BAR; PG8_MMA(1, 0, At, B0); PG8_MMA(1, 1, At, B1); PG8_BAR; PG8_SCHED;
;         }
	s_mov_b32 m0, s76
	v_lshl_add_u64 v[150:151], v[150:151], 0, s[82:83]
	ds_read_b128 v[202:205], v152 offset:49152
	ds_read_b128 v[206:209], v152 offset:50176
	ds_read_b128 v[226:229], v152 offset:51200
	ds_read_b128 v[230:233], v152 offset:52224
	ds_read_b128 v[234:237], v152 offset:53248
	ds_read_b128 v[238:241], v152 offset:54272
	ds_read_b128 v[242:245], v152 offset:55296
	ds_read_b128 v[246:249], v152 offset:56320
	global_load_lds_dwordx4 v[150:151], off
	v_lshl_add_u64 v[150:151], v[210:211], 0, s[82:83]
	s_mov_b32 m0, s80
	s_nop 0
	global_load_lds_dwordx4 v[150:151], off
	v_lshl_add_u64 v[150:151], v[250:251], 0, s[82:83]
	s_mov_b32 m0, s92
	s_nop 0
	global_load_lds_dwordx4 v[150:151], off
	v_lshl_add_u64 v[150:151], v[252:253], 0, s[82:83]
	s_mov_b32 m0, s93
	s_nop 0
	global_load_lds_dwordx4 v[150:151], off
	v_lshl_add_u64 v[150:151], v[218:219], 0, s[82:83]
	s_mov_b32 m0, s81
	s_nop 0
	global_load_lds_dwordx4 v[150:151], off
	v_lshl_add_u64 v[150:151], v[216:217], 0, s[82:83]
	s_mov_b32 m0, s91
	s_nop 0
	global_load_lds_dwordx4 v[150:151], off
	s_waitcnt vmcnt(8)
	s_waitcnt lgkmcnt(0)
	s_barrier
	s_waitcnt lgkmcnt(0)
	v_mfma_f32_16x16x32_bf16 v[60:63], v[170:173], v[202:205], v[60:63]
	v_mfma_f32_16x16x32_bf16 v[56:59], v[178:181], v[202:205], v[56:59]
	v_mfma_f32_16x16x32_bf16 v[44:47], v[170:173], v[226:229], v[44:47]
	v_mfma_f32_16x16x32_bf16 v[40:43], v[178:181], v[226:229], v[40:43]
	v_mfma_f32_16x16x32_bf16 v[28:31], v[170:173], v[234:237], v[28:31]
	v_mfma_f32_16x16x32_bf16 v[24:27], v[178:181], v[234:237], v[24:27]
	v_mfma_f32_16x16x32_bf16 v[12:15], v[170:173], v[242:245], v[12:15]
	v_mfma_f32_16x16x32_bf16 v[8:11], v[178:181], v[242:245], v[8:11]
	v_mfma_f32_16x16x32_bf16 v[60:63], v[174:177], v[206:209], v[60:63]
	v_mfma_f32_16x16x32_bf16 v[56:59], v[182:185], v[206:209], v[56:59]
	v_mfma_f32_16x16x32_bf16 v[44:47], v[174:177], v[230:233], v[44:47]
	v_mfma_f32_16x16x32_bf16 v[40:43], v[182:185], v[230:233], v[40:43]
	v_mfma_f32_16x16x32_bf16 v[28:31], v[174:177], v[238:241], v[28:31]
	v_mfma_f32_16x16x32_bf16 v[24:27], v[182:185], v[238:241], v[24:27]
	v_mfma_f32_16x16x32_bf16 v[12:15], v[174:177], v[246:249], v[12:15]
	v_mfma_f32_16x16x32_bf16 v[8:11], v[182:185], v[246:249], v[8:11]
	v_mfma_f32_16x16x32_bf16 v[52:55], v[186:189], v[202:205], v[52:55]
	v_mfma_f32_16x16x32_bf16 v[48:51], v[194:197], v[202:205], v[48:51]
	v_mfma_f32_16x16x32_bf16 v[36:39], v[186:189], v[226:229], v[36:39]
	v_mfma_f32_16x16x32_bf16 v[32:35], v[194:197], v[226:229], v[32:35]
	v_mfma_f32_16x16x32_bf16 v[20:23], v[186:189], v[234:237], v[20:23]
	v_mfma_f32_16x16x32_bf16 v[16:19], v[194:197], v[234:237], v[16:19]
	v_mfma_f32_16x16x32_bf16 v[4:7], v[186:189], v[242:245], v[4:7]
	v_mfma_f32_16x16x32_bf16 v[0:3], v[194:197], v[242:245], v[0:3]
	v_mfma_f32_16x16x32_bf16 v[52:55], v[190:193], v[206:209], v[52:55]
	v_mfma_f32_16x16x32_bf16 v[48:51], v[198:201], v[206:209], v[48:51]
	v_mfma_f32_16x16x32_bf16 v[36:39], v[190:193], v[230:233], v[36:39]
	v_mfma_f32_16x16x32_bf16 v[32:35], v[198:201], v[230:233], v[32:35]
	v_mfma_f32_16x16x32_bf16 v[20:23], v[190:193], v[238:241], v[20:23]
	v_mfma_f32_16x16x32_bf16 v[16:19], v[198:201], v[238:241], v[16:19]
	v_mfma_f32_16x16x32_bf16 v[4:7], v[190:193], v[246:249], v[4:7]
	v_mfma_f32_16x16x32_bf16 v[0:3], v[198:201], v[246:249], v[0:3]
	s_barrier
	s_add_u32 s2, s2, 0x100
	s_addc_u32 s3, s3, 0
	s_add_u32 s48, s48, 0x100
	s_addc_u32 s49, s49, 0
	s_cmp_ge_i32 s56, s94
	s_cbranch_scc1 .LBB0_252

; #define PG8_STAGE(bufoff, gbase, voff) do { _Pragma("unroll") for (int _i = 0; _i < 2; ++_i) \
;         __builtin_amdgcn_global_load_lds((const unsigned*)((const char*)(gbase) + (voff)[_i]), (LAS unsigned*)(lds + (bufoff) + ldsw + _i * 8192), 16, 0, 0); } while (0)
; #define PG8_LDA(dst, b, h) do { _Pragma("unroll") for (int m = 0; m < 4; ++m) _Pragma("unroll") for (int k = 0; k < 2; ++k) dst[m][k] = *(const LAS bf16x8*)(lds + PG8_SA(b, h) + aoff + m * 2048 + k * 1024); } while (0)
; #define PG8_LDB(dst, b, h) do { _Pragma("unroll") for (int n = 0; n < 2; ++n) _Pragma("unroll") for (int k = 0; k < 2; ++k) dst[n][k] = *(const LAS bf16x8*)(lds + PG8_SB(b, h) + boff + n * 2048 + k * 1024); } while (0)
; #define PG8_MMA(ai, bj, At, Bt) do { __builtin_amdgcn_s_setprio(1); _Pragma("unroll") for (int m = 0; m < 4; ++m) _Pragma("unroll") for (int n = 0; n < 2; ++n) _Pragma("unroll") for (int k = 0; k < 2; ++k) \
;         acc[ai][bj][m][n] = __builtin_amdgcn_mfma_f32_16x16x32_bf16(Bt[n][k], At[m][k], acc[ai][bj][m][n], 0, 0, 0); __builtin_amdgcn_s_setprio(0); } while (0)
; #define PG8_WAIT_V(n) asm volatile("s_waitcnt vmcnt(" #n ")" ::: "memory")
; #define PG8_WAIT_L(n) asm volatile("s_waitcnt lgkmcnt(" #n ")" ::: "memory")
; #define PG8_BAR __builtin_amdgcn_s_barrier()
; #define PG8_SCHED __builtin_amdgcn_sched_barrier(0)
; template <class Epi>
; __device__ __forceinline__ void gemm_phase(LAS unsigned char* lds, const Gemm g, const StaticOrder& S, const Epi& E) {
;     ...
;             PG8_LDB(B0, 0, 0); PG8_LDB(B1, 0, 1); PG8_SCHED; PG8_LDA(At, 0, 0); PG8_STAGE(PG8_SA(1, 1), a1 + hstep, voffA);
;             PG8_WAIT_V(8); PG8_WAIT_L(0); PG8_BAR; PG8_MMA(0, 0, At, B0); PG8_MMA(0, 1, At, B1); PG8_BAR; PG8_SCHED;
;             PG8_LDA(At, 0, 1); PG8_STAGE(PG8_SB(0, 0), b2, voffB); PG8_STAGE(PG8_SB(0, 1), b2 + hstep, voffB); PG8_STAGE(PG8_SA(0, 0), a2, voffA);
;             PG8_WAIT_V(8); PG8_WAIT_L(0); PG8_BAR; PG8_MMA(1, 0, At, B0); PG8_MMA(1, 1, At, B1); PG8_BAR; PG8_SCHED;
.LBB0_406:
	s_or_b64 exec, exec, s[38:39]
	v_or_b32_e32 v131, 0x10000, v163
	v_add_u32_e32 v151, 0x10400, v163
	ds_read_b128 v[168:171], v131
	ds_read_b128 v[172:175], v151
	v_add_u32_e32 v131, 0x10800, v163
	v_add_u32_e32 v151, 0x10c00, v163
	ds_read_b128 v[176:179], v131
	ds_read_b128 v[180:183], v151
	v_or_b32_e32 v131, 0x14000, v163
	v_add_u32_e32 v151, 0x14400, v163
	ds_read_b128 v[184:187], v131
	ds_read_b128 v[188:191], v151
	v_add_u32_e32 v131, 0x14800, v163
	v_add_u32_e32 v151, 0x14c00, v163
	ds_read_b128 v[192:195], v131
	ds_read_b128 v[196:199], v151
	s_add_i32 s64, s64, 2
	s_add_u32 s38, s2, 0x80
	s_addc_u32 s39, s3, 0
	s_and_b64 s[8:9], s[8:9], exec
	s_cselect_b32 s9, s39, s11
	s_cselect_b32 s8, s38, s10
	s_cselect_b32 s39, s57, s37
	s_cselect_b32 s38, s56, s36
	v_lshl_add_u64 v[152:153], s[2:3], 0, v[146:147]
	s_add_i32 m0, s40, 0xc000
	ds_read_b128 v[200:203], v162
	ds_read_b128 v[204:207], v162 offset:1024
	ds_read_b128 v[208:211], v162 offset:2048
	ds_read_b128 v[226:229], v162 offset:3072
	ds_read_b128 v[230:233], v162 offset:4096
	ds_read_b128 v[234:237], v162 offset:5120
	ds_read_b128 v[238:241], v162 offset:6144
	ds_read_b128 v[242:245], v162 offset:7168
	global_load_lds_dwordx4 v[152:153], off
	v_lshl_add_u64 v[152:153], s[2:3], 0, v[148:149]
	s_add_i32 m0, s40, 0xe000
	s_nop 0
	global_load_lds_dwordx4 v[152:153], off
	s_waitcnt vmcnt(8)
	s_waitcnt lgkmcnt(0)
	s_barrier
	s_waitcnt lgkmcnt(0)
	v_mfma_f32_16x16x32_bf16 v[124:127], v[168:171], v[200:203], v[124:127]
	v_mfma_f32_16x16x32_bf16 v[120:123], v[176:179], v[200:203], v[120:123]
	v_mfma_f32_16x16x32_bf16 v[108:111], v[168:171], v[208:211], v[108:111]
	v_mfma_f32_16x16x32_bf16 v[104:107], v[176:179], v[208:211], v[104:107]
	v_mfma_f32_16x16x32_bf16 v[92:95], v[168:171], v[230:233], v[92:95]
	v_mfma_f32_16x16x32_bf16 v[88:91], v[176:179], v[230:233], v[88:91]
	v_mfma_f32_16x16x32_bf16 v[76:79], v[168:171], v[238:241], v[76:79]
	v_mfma_f32_16x16x32_bf16 v[72:75], v[176:179], v[238:241], v[72:75]
	v_mfma_f32_16x16x32_bf16 v[124:127], v[172:175], v[204:207], v[124:127]
	v_mfma_f32_16x16x32_bf16 v[120:123], v[180:183], v[204:207], v[120:123]
	v_mfma_f32_16x16x32_bf16 v[108:111], v[172:175], v[226:229], v[108:111]
	v_mfma_f32_16x16x32_bf16 v[104:107], v[180:183], v[226:229], v[104:107]
	v_mfma_f32_16x16x32_bf16 v[92:95], v[172:175], v[234:237], v[92:95]
	v_mfma_f32_16x16x32_bf16 v[88:91], v[180:183], v[234:237], v[88:91]
	v_mfma_f32_16x16x32_bf16 v[76:79], v[172:175], v[242:245], v[76:79]
	v_mfma_f32_16x16x32_bf16 v[72:75], v[180:183], v[242:245], v[72:75]
	v_mfma_f32_16x16x32_bf16 v[116:119], v[184:187], v[200:203], v[116:119]
	v_mfma_f32_16x16x32_bf16 v[112:115], v[192:195], v[200:203], v[112:115]
	v_mfma_f32_16x16x32_bf16 v[100:103], v[184:187], v[208:211], v[100:103]
	v_mfma_f32_16x16x32_bf16 v[96:99], v[192:195], v[208:211], v[96:99]
	v_mfma_f32_16x16x32_bf16 v[84:87], v[184:187], v[230:233], v[84:87]
	v_mfma_f32_16x16x32_bf16 v[80:83], v[192:195], v[230:233], v[80:83]
	v_mfma_f32_16x16x32_bf16 v[68:71], v[184:187], v[238:241], v[68:71]
	v_mfma_f32_16x16x32_bf16 v[64:67], v[192:195], v[238:241], v[64:67]
	v_mfma_f32_16x16x32_bf16 v[116:119], v[188:191], v[204:207], v[116:119]
	v_mfma_f32_16x16x32_bf16 v[112:115], v[196:199], v[204:207], v[112:115]
	v_mfma_f32_16x16x32_bf16 v[100:103], v[188:191], v[226:229], v[100:103]
	v_mfma_f32_16x16x32_bf16 v[96:99], v[196:199], v[226:229], v[96:99]
	v_mfma_f32_16x16x32_bf16 v[84:87], v[188:191], v[234:237], v[84:87]
	v_mfma_f32_16x16x32_bf16 v[80:83], v[196:199], v[234:237], v[80:83]
	v_mfma_f32_16x16x32_bf16 v[68:71], v[188:191], v[242:245], v[68:71]
	v_mfma_f32_16x16x32_bf16 v[64:67], v[196:199], v[242:245], v[64:67]
	s_barrier
	s_mov_b32 m0, s41
	v_lshl_add_u64 v[152:153], s[38:39], 0, v[134:135]
	v_lshl_add_u64 v[216:217], s[38:39], 0, v[138:139]
	s_add_u32 s38, s38, s24
	ds_read_b128 v[200:203], v162 offset:16384
	ds_read_b128 v[204:207], v162 offset:17408
	ds_read_b128 v[208:211], v162 offset:18432
	ds_read_b128 v[226:229], v162 offset:19456
	ds_read_b128 v[230:233], v162 offset:20480
	ds_read_b128 v[234:237], v162 offset:21504
	ds_read_b128 v[238:241], v162 offset:22528
	ds_read_b128 v[242:245], v162 offset:23552
	global_load_lds_dwordx4 v[152:153], off
	s_mov_b32 m0, s42
	s_addc_u32 s39, s39, s25
	global_load_lds_dwordx4 v[216:217], off
	v_lshl_add_u64 v[218:219], s[38:39], 0, v[134:135]
	s_mov_b32 m0, s43
	v_lshl_add_u64 v[220:221], s[38:39], 0, v[138:139]
	global_load_lds_dwordx4 v[218:219], off
	s_mov_b32 m0, s44
	v_lshl_add_u64 v[246:247], s[8:9], 0, v[132:133]
	global_load_lds_dwordx4 v[220:221], off
	s_mov_b32 m0, s40
	v_lshl_add_u64 v[248:249], s[8:9], 0, v[136:137]
	global_load_lds_dwordx4 v[246:247], off
	s_mov_b32 m0, s45
	s_nop 0
	global_load_lds_dwordx4 v[248:249], off
	s_waitcnt vmcnt(8)
	s_waitcnt lgkmcnt(0)
	s_barrier
; #define PG8_STAGE(bufoff, gbase, voff) do { _Pragma("unroll") for (int _i = 0; _i < 2; ++_i) \
;         __builtin_amdgcn_global_load_lds((const unsigned*)((const char*)(gbase) + (voff)[_i]), (LAS unsigned*)(lds + (bufoff) + ldsw + _i * 8192), 16, 0, 0); } while (0)
; #define PG8_LDA(dst, b, h) do { _Pragma("unroll") for (int m = 0; m < 4; ++m) _Pragma("unroll") for (int k = 0; k < 2; ++k) dst[m][k] = *(const LAS bf16x8*)(lds + PG8_SA(b, h) + aoff + m * 2048 + k * 1024); } while (0)
; #define PG8_LDB(dst, b, h) do { _Pragma("unroll") for (int n = 0; n < 2; ++n) _Pragma("unroll") for (int k = 0; k < 2; ++k) dst[n][k] = *(const LAS bf16x8*)(lds + PG8_SB(b, h) + boff + n * 2048 + k * 1024); } while (0)
; #define PG8_MMA(ai, bj, At, Bt) do { __builtin_amdgcn_s_setprio(1); _Pragma("unroll") for (int m = 0; m < 4; ++m) _Pragma("unroll") for (int n = 0; n < 2; ++n) _Pragma("unroll") for (int k = 0; k < 2; ++k) \
;         acc[ai][bj][m][n] = __builtin_amdgcn_mfma_f32_16x16x32_bf16(Bt[n][k], At[m][k], acc[ai][bj][m][n], 0, 0, 0); __builtin_amdgcn_s_setprio(0); } while (0)
; #define PG8_WAIT_V(n) asm volatile("s_waitcnt vmcnt(" #n ")" ::: "memory")
; #define PG8_WAIT_L(n) asm volatile("s_waitcnt lgkmcnt(" #n ")" ::: "memory")
; #define PG8_BAR __builtin_amdgcn_s_barrier()
; #define PG8_SCHED __builtin_amdgcn_sched_barrier(0)
; template <class Epi>
; __device__ __forceinline__ void gemm_phase(LAS unsigned char* lds, const Gemm g, const StaticOrder& S, const Epi& E) {
;     ...
;             PG8_WAIT_V(8); PG8_WAIT_L(0); PG8_BAR; PG8_MMA(1, 0, At, B0); PG8_MMA(1, 1, At, B1); PG8_BAR; PG8_SCHED;
;             PG8_LDB(B0, 1, 0); PG8_LDB(B1, 1, 1); PG8_SCHED; PG8_LDA(At, 1, 0); PG8_STAGE(PG8_SA(0, 1), a2 + hstep, voffA);
;             PG8_WAIT_V(8); PG8_WAIT_L(0); PG8_BAR; PG8_MMA(0, 0, At, B0); PG8_MMA(0, 1, At, B1); PG8_BAR; PG8_SCHED;
	s_waitcnt lgkmcnt(0)
	v_mfma_f32_16x16x32_bf16 v[60:63], v[168:171], v[200:203], v[60:63]
	v_mfma_f32_16x16x32_bf16 v[56:59], v[176:179], v[200:203], v[56:59]
	v_mfma_f32_16x16x32_bf16 v[44:47], v[168:171], v[208:211], v[44:47]
	v_mfma_f32_16x16x32_bf16 v[40:43], v[176:179], v[208:211], v[40:43]
	v_mfma_f32_16x16x32_bf16 v[28:31], v[168:171], v[230:233], v[28:31]
	v_mfma_f32_16x16x32_bf16 v[24:27], v[176:179], v[230:233], v[24:27]
	v_mfma_f32_16x16x32_bf16 v[12:15], v[168:171], v[238:241], v[12:15]
	v_mfma_f32_16x16x32_bf16 v[8:11], v[176:179], v[238:241], v[8:11]
	v_mfma_f32_16x16x32_bf16 v[60:63], v[172:175], v[204:207], v[60:63]
	v_mfma_f32_16x16x32_bf16 v[56:59], v[180:183], v[204:207], v[56:59]
	v_mfma_f32_16x16x32_bf16 v[44:47], v[172:175], v[226:229], v[44:47]
	v_mfma_f32_16x16x32_bf16 v[40:43], v[180:183], v[226:229], v[40:43]
	v_mfma_f32_16x16x32_bf16 v[28:31], v[172:175], v[234:237], v[28:31]
	v_mfma_f32_16x16x32_bf16 v[24:27], v[180:183], v[234:237], v[24:27]
	v_mfma_f32_16x16x32_bf16 v[12:15], v[172:175], v[242:245], v[12:15]
	v_mfma_f32_16x16x32_bf16 v[8:11], v[180:183], v[242:245], v[8:11]
	v_mfma_f32_16x16x32_bf16 v[52:55], v[184:187], v[200:203], v[52:55]
	v_mfma_f32_16x16x32_bf16 v[48:51], v[192:195], v[200:203], v[48:51]
	v_mfma_f32_16x16x32_bf16 v[36:39], v[184:187], v[208:211], v[36:39]
	v_mfma_f32_16x16x32_bf16 v[32:35], v[192:195], v[208:211], v[32:35]
	v_mfma_f32_16x16x32_bf16 v[20:23], v[184:187], v[230:233], v[20:23]
	v_mfma_f32_16x16x32_bf16 v[16:19], v[192:195], v[230:233], v[16:19]
	v_mfma_f32_16x16x32_bf16 v[4:7], v[184:187], v[238:241], v[4:7]
	v_mfma_f32_16x16x32_bf16 v[0:3], v[192:195], v[238:241], v[0:3]
	v_mfma_f32_16x16x32_bf16 v[52:55], v[188:191], v[204:207], v[52:55]
	v_mfma_f32_16x16x32_bf16 v[48:51], v[196:199], v[204:207], v[48:51]
	v_mfma_f32_16x16x32_bf16 v[36:39], v[188:191], v[226:229], v[36:39]
	v_mfma_f32_16x16x32_bf16 v[32:35], v[196:199], v[226:229], v[32:35]
	v_mfma_f32_16x16x32_bf16 v[20:23], v[188:191], v[234:237], v[20:23]
	v_mfma_f32_16x16x32_bf16 v[16:19], v[196:199], v[234:237], v[16:19]
	v_mfma_f32_16x16x32_bf16 v[4:7], v[188:191], v[242:245], v[4:7]
	v_mfma_f32_16x16x32_bf16 v[0:3], v[196:199], v[242:245], v[0:3]
	s_barrier
	v_or_b32_e32 v131, 0x18000, v163
	v_add_u32_e32 v151, 0x18400, v163
	ds_read_b128 v[168:171], v131
	ds_read_b128 v[172:175], v151
	v_add_u32_e32 v131, 0x18800, v163
	v_add_u32_e32 v151, 0x18c00, v163
	ds_read_b128 v[176:179], v131
	ds_read_b128 v[180:183], v151
	v_or_b32_e32 v131, 0x1c000, v163
	v_add_u32_e32 v151, 0x1c400, v163
	ds_read_b128 v[184:187], v131
	ds_read_b128 v[188:191], v151
	v_add_u32_e32 v131, 0x1c800, v163
	v_add_u32_e32 v151, 0x1cc00, v163
	ds_read_b128 v[192:195], v131
	ds_read_b128 v[196:199], v151
	s_add_u32 s8, s8, s24
	s_addc_u32 s9, s9, s25
	s_mov_b32 m0, s46
	v_lshl_add_u64 v[250:251], s[8:9], 0, v[132:133]
	ds_read_b128 v[200:203], v162 offset:32768
	ds_read_b128 v[204:207], v162 offset:33792
	ds_read_b128 v[208:211], v162 offset:34816
	ds_read_b128 v[226:229], v162 offset:35840
	ds_read_b128 v[230:233], v162 offset:36864
	ds_read_b128 v[234:237], v162 offset:37888
	ds_read_b128 v[238:241], v162 offset:38912
	ds_read_b128 v[242:245], v162 offset:39936
	global_load_lds_dwordx4 v[250:251], off
	v_lshl_add_u64 v[250:251], s[8:9], 0, v[136:137]
	s_mov_b32 m0, s47
	s_nop 0
	global_load_lds_dwordx4 v[250:251], off
	s_waitcnt vmcnt(8)
	s_waitcnt lgkmcnt(0)
	s_barrier
	s_waitcnt lgkmcnt(0)
	v_mfma_f32_16x16x32_bf16 v[124:127], v[168:171], v[200:203], v[124:127]
	v_mfma_f32_16x16x32_bf16 v[120:123], v[176:179], v[200:203], v[120:123]
	v_mfma_f32_16x16x32_bf16 v[108:111], v[168:171], v[208:211], v[108:111]
	v_mfma_f32_16x16x32_bf16 v[104:107], v[176:179], v[208:211], v[104:107]
	v_mfma_f32_16x16x32_bf16 v[92:95], v[168:171], v[230:233], v[92:95]
	v_mfma_f32_16x16x32_bf16 v[88:91], v[176:179], v[230:233], v[88:91]
	v_mfma_f32_16x16x32_bf16 v[76:79], v[168:171], v[238:241], v[76:79]
	v_mfma_f32_16x16x32_bf16 v[72:75], v[176:179], v[238:241], v[72:75]
	v_mfma_f32_16x16x32_bf16 v[124:127], v[172:175], v[204:207], v[124:127]
	v_mfma_f32_16x16x32_bf16 v[120:123], v[180:183], v[204:207], v[120:123]
	v_mfma_f32_16x16x32_bf16 v[108:111], v[172:175], v[226:229], v[108:111]
	v_mfma_f32_16x16x32_bf16 v[104:107], v[180:183], v[226:229], v[104:107]
	v_mfma_f32_16x16x32_bf16 v[92:95], v[172:175], v[234:237], v[92:95]
	v_mfma_f32_16x16x32_bf16 v[88:91], v[180:183], v[234:237], v[88:91]
	v_mfma_f32_16x16x32_bf16 v[76:79], v[172:175], v[242:245], v[76:79]
	v_mfma_f32_16x16x32_bf16 v[72:75], v[180:183], v[242:245], v[72:75]
	v_mfma_f32_16x16x32_bf16 v[116:119], v[184:187], v[200:203], v[116:119]
	v_mfma_f32_16x16x32_bf16 v[112:115], v[192:195], v[200:203], v[112:115]
	v_mfma_f32_16x16x32_bf16 v[100:103], v[184:187], v[208:211], v[100:103]
	v_mfma_f32_16x16x32_bf16 v[96:99], v[192:195], v[208:211], v[96:99]
	v_mfma_f32_16x16x32_bf16 v[84:87], v[184:187], v[230:233], v[84:87]
	v_mfma_f32_16x16x32_bf16 v[80:83], v[192:195], v[230:233], v[80:83]
	v_mfma_f32_16x16x32_bf16 v[68:71], v[184:187], v[238:241], v[68:71]
	v_mfma_f32_16x16x32_bf16 v[64:67], v[192:195], v[238:241], v[64:67]
	v_mfma_f32_16x16x32_bf16 v[116:119], v[188:191], v[204:207], v[116:119]
	v_mfma_f32_16x16x32_bf16 v[112:115], v[196:199], v[204:207], v[112:115]
	v_mfma_f32_16x16x32_bf16 v[100:103], v[188:191], v[226:229], v[100:103]
	v_mfma_f32_16x16x32_bf16 v[96:99], v[196:199], v[226:229], v[96:99]
	v_mfma_f32_16x16x32_bf16 v[84:87], v[188:191], v[234:237], v[84:87]
	v_mfma_f32_16x16x32_bf16 v[80:83], v[196:199], v[234:237], v[80:83]
	v_mfma_f32_16x16x32_bf16 v[68:71], v[188:191], v[242:245], v[68:71]
	v_mfma_f32_16x16x32_bf16 v[64:67], v[196:199], v[242:245], v[64:67]
	s_barrier
; #define PG8_STAGE(bufoff, gbase, voff) do { _Pragma("unroll") for (int _i = 0; _i < 2; ++_i) \
;         __builtin_amdgcn_global_load_lds((const unsigned*)((const char*)(gbase) + (voff)[_i]), (LAS unsigned*)(lds + (bufoff) + ldsw + _i * 8192), 16, 0, 0); } while (0)
; #define PG8_LDA(dst, b, h) do { _Pragma("unroll") for (int m = 0; m < 4; ++m) _Pragma("unroll") for (int k = 0; k < 2; ++k) dst[m][k] = *(const LAS bf16x8*)(lds + PG8_SA(b, h) + aoff + m * 2048 + k * 1024); } while (0)
; #define PG8_MMA(ai, bj, At, Bt) do { __builtin_amdgcn_s_setprio(1); _Pragma("unroll") for (int m = 0; m < 4; ++m) _Pragma("unroll") for (int n = 0; n < 2; ++n) _Pragma("unroll") for (int k = 0; k < 2; ++k) \
;         acc[ai][bj][m][n] = __builtin_amdgcn_mfma_f32_16x16x32_bf16(Bt[n][k], At[m][k], acc[ai][bj][m][n], 0, 0, 0); __builtin_amdgcn_s_setprio(0); } while (0)
; #define PG8_WAIT_V(n) asm volatile("s_waitcnt vmcnt(" #n ")" ::: "memory")
; #define PG8_WAIT_L(n) asm volatile("s_waitcnt lgkmcnt(" #n ")" ::: "memory")
; #define PG8_BAR __builtin_amdgcn_s_barrier()
; #define PG8_SCHED __builtin_amdgcn_sched_barrier(0)
; template <class Epi>
; __device__ __forceinline__ void gemm_phase(LAS unsigned char* lds, const Gemm g, const StaticOrder& S, const Epi& E) {
;     ...
;             PG8_LDA(At, 1, 1); PG8_STAGE(PG8_SB(1, 0), b3, voffB); PG8_STAGE(PG8_SB(1, 1), b3 + hstep, voffB); PG8_STAGE(PG8_SA(1, 0), a3, voffA);
;             PG8_WAIT_V(8); PG8_WAIT_L(0); PG8_BAR; PG8_MMA(1, 0, At, B0); PG8_MMA(1, 1, At, B1); PG8_BAR; PG8_SCHED;
;         }
	s_mov_b32 m0, s48
	v_lshl_add_u64 v[152:153], v[152:153], 0, s[82:83]
	ds_read_b128 v[200:203], v162 offset:49152
	ds_read_b128 v[204:207], v162 offset:50176
	ds_read_b128 v[208:211], v162 offset:51200
	ds_read_b128 v[226:229], v162 offset:52224
	ds_read_b128 v[230:233], v162 offset:53248
	ds_read_b128 v[234:237], v162 offset:54272
	ds_read_b128 v[238:241], v162 offset:55296
	ds_read_b128 v[242:245], v162 offset:56320
	global_load_lds_dwordx4 v[152:153], off
	v_lshl_add_u64 v[152:153], v[216:217], 0, s[82:83]
	s_mov_b32 m0, s49
	s_nop 0
	global_load_lds_dwordx4 v[152:153], off
	v_lshl_add_u64 v[152:153], v[218:219], 0, s[82:83]
	s_mov_b32 m0, s52
	s_nop 0
	global_load_lds_dwordx4 v[152:153], off
	v_lshl_add_u64 v[152:153], v[220:221], 0, s[82:83]
	s_mov_b32 m0, s53
	s_nop 0
	global_load_lds_dwordx4 v[152:153], off
	v_lshl_add_u64 v[152:153], v[246:247], 0, s[82:83]
	s_mov_b32 m0, s50
	s_nop 0
	global_load_lds_dwordx4 v[152:153], off
	v_lshl_add_u64 v[152:153], v[248:249], 0, s[82:83]
	s_mov_b32 m0, s51
	s_nop 0
	global_load_lds_dwordx4 v[152:153], off
	s_waitcnt vmcnt(8)
	s_waitcnt lgkmcnt(0)
	s_barrier
	s_waitcnt lgkmcnt(0)
	v_mfma_f32_16x16x32_bf16 v[60:63], v[168:171], v[200:203], v[60:63]
	v_mfma_f32_16x16x32_bf16 v[56:59], v[176:179], v[200:203], v[56:59]
	v_mfma_f32_16x16x32_bf16 v[44:47], v[168:171], v[208:211], v[44:47]
	v_mfma_f32_16x16x32_bf16 v[40:43], v[176:179], v[208:211], v[40:43]
	v_mfma_f32_16x16x32_bf16 v[28:31], v[168:171], v[230:233], v[28:31]
	v_mfma_f32_16x16x32_bf16 v[24:27], v[176:179], v[230:233], v[24:27]
	v_mfma_f32_16x16x32_bf16 v[12:15], v[168:171], v[238:241], v[12:15]
	v_mfma_f32_16x16x32_bf16 v[8:11], v[176:179], v[238:241], v[8:11]
	v_mfma_f32_16x16x32_bf16 v[60:63], v[172:175], v[204:207], v[60:63]
	v_mfma_f32_16x16x32_bf16 v[56:59], v[180:183], v[204:207], v[56:59]
	v_mfma_f32_16x16x32_bf16 v[44:47], v[172:175], v[226:229], v[44:47]
	v_mfma_f32_16x16x32_bf16 v[40:43], v[180:183], v[226:229], v[40:43]
	v_mfma_f32_16x16x32_bf16 v[28:31], v[172:175], v[234:237], v[28:31]
	v_mfma_f32_16x16x32_bf16 v[24:27], v[180:183], v[234:237], v[24:27]
	v_mfma_f32_16x16x32_bf16 v[12:15], v[172:175], v[242:245], v[12:15]
	v_mfma_f32_16x16x32_bf16 v[8:11], v[180:183], v[242:245], v[8:11]
	v_mfma_f32_16x16x32_bf16 v[52:55], v[184:187], v[200:203], v[52:55]
	v_mfma_f32_16x16x32_bf16 v[48:51], v[192:195], v[200:203], v[48:51]
	v_mfma_f32_16x16x32_bf16 v[36:39], v[184:187], v[208:211], v[36:39]
	v_mfma_f32_16x16x32_bf16 v[32:35], v[192:195], v[208:211], v[32:35]
	v_mfma_f32_16x16x32_bf16 v[20:23], v[184:187], v[230:233], v[20:23]
	v_mfma_f32_16x16x32_bf16 v[16:19], v[192:195], v[230:233], v[16:19]
	v_mfma_f32_16x16x32_bf16 v[4:7], v[184:187], v[238:241], v[4:7]
	v_mfma_f32_16x16x32_bf16 v[0:3], v[192:195], v[238:241], v[0:3]
	v_mfma_f32_16x16x32_bf16 v[52:55], v[188:191], v[204:207], v[52:55]
	v_mfma_f32_16x16x32_bf16 v[48:51], v[196:199], v[204:207], v[48:51]
	v_mfma_f32_16x16x32_bf16 v[36:39], v[188:191], v[226:229], v[36:39]
	v_mfma_f32_16x16x32_bf16 v[32:35], v[196:199], v[226:229], v[32:35]
	v_mfma_f32_16x16x32_bf16 v[20:23], v[188:191], v[234:237], v[20:23]
	v_mfma_f32_16x16x32_bf16 v[16:19], v[196:199], v[234:237], v[16:19]
	v_mfma_f32_16x16x32_bf16 v[4:7], v[188:191], v[242:245], v[4:7]
	v_mfma_f32_16x16x32_bf16 v[0:3], v[196:199], v[242:245], v[0:3]
	s_barrier
	s_add_u32 s2, s2, 0x100
	s_addc_u32 s3, s3, 0
	s_add_u32 s56, s56, 0x100
	s_addc_u32 s57, s57, 0
	s_cmp_ge_i32 s64, s54
	s_cbranch_scc1 .LBB0_409

; #define PG8_STAGE(bufoff, gbase, voff) do { _Pragma("unroll") for (int _i = 0; _i < 2; ++_i) \
;         __builtin_amdgcn_global_load_lds((const unsigned*)((const char*)(gbase) + (voff)[_i]), (LAS unsigned*)(lds + (bufoff) + ldsw + _i * 8192), 16, 0, 0); } while (0)
; #define PG8_LDA(dst, b, h) do { _Pragma("unroll") for (int m = 0; m < 4; ++m) _Pragma("unroll") for (int k = 0; k < 2; ++k) dst[m][k] = *(const LAS bf16x8*)(lds + PG8_SA(b, h) + aoff + m * 2048 + k * 1024); } while (0)
; #define PG8_LDB(dst, b, h) do { _Pragma("unroll") for (int n = 0; n < 2; ++n) _Pragma("unroll") for (int k = 0; k < 2; ++k) dst[n][k] = *(const LAS bf16x8*)(lds + PG8_SB(b, h) + boff + n * 2048 + k * 1024); } while (0)
; #define PG8_MMA(ai, bj, At, Bt) do { __builtin_amdgcn_s_setprio(1); _Pragma("unroll") for (int m = 0; m < 4; ++m) _Pragma("unroll") for (int n = 0; n < 2; ++n) _Pragma("unroll") for (int k = 0; k < 2; ++k) \
;         acc[ai][bj][m][n] = __builtin_amdgcn_mfma_f32_16x16x32_bf16(Bt[n][k], At[m][k], acc[ai][bj][m][n], 0, 0, 0); __builtin_amdgcn_s_setprio(0); } while (0)
; #define PG8_WAIT_V(n) asm volatile("s_waitcnt vmcnt(" #n ")" ::: "memory")
; #define PG8_WAIT_L(n) asm volatile("s_waitcnt lgkmcnt(" #n ")" ::: "memory")
; #define PG8_BAR __builtin_amdgcn_s_barrier()
; #define PG8_SCHED __builtin_amdgcn_sched_barrier(0)
; template <class Epi>
; __device__ __forceinline__ void gemm_phase(LAS unsigned char* lds, const Gemm g, const StaticOrder& S, const Epi& E) {
;     ...
;             PG8_LDB(B0, 0, 0); PG8_LDB(B1, 0, 1); PG8_SCHED; PG8_LDA(At, 0, 0); PG8_STAGE(PG8_SA(1, 1), a1 + hstep, voffA);
;             PG8_WAIT_V(8); PG8_WAIT_L(0); PG8_BAR; PG8_MMA(0, 0, At, B0); PG8_MMA(0, 1, At, B1); PG8_BAR; PG8_SCHED;
;             PG8_LDA(At, 0, 1); PG8_STAGE(PG8_SB(0, 0), b2, voffB); PG8_STAGE(PG8_SB(0, 1), b2 + hstep, voffB); PG8_STAGE(PG8_SA(0, 0), a2, voffA);
.LBB0_768:
	v_or_b32_e32 v142, 0x10000, v140
	v_add_u32_e32 v146, 0x10400, v140
	v_add_u32_e32 v150, 0x10800, v140
	v_add_u32_e32 v154, 0x10c00, v140
	ds_read_b128 v[142:145], v142
	ds_read_b128 v[146:149], v146
	ds_read_b128 v[150:153], v150
	ds_read_b128 v[162:165], v154
	v_or_b32_e32 v154, 0x14000, v140
	v_add_u32_e32 v155, 0x14400, v140
	ds_read_b128 v[166:169], v154
	ds_read_b128 v[170:173], v155
	v_add_u32_e32 v154, 0x14800, v140
	s_add_i32 s57, s22, 2
	v_add_u32_e32 v155, 0x14c00, v140
	ds_read_b128 v[174:177], v154
	ds_read_b128 v[178:181], v155
	s_add_u32 s58, s20, 0x80
	s_addc_u32 s23, s21, 0
	s_cmp_eq_u32 s49, s22
	s_cselect_b32 s22, s0, s58
	s_cselect_b32 s23, s1, s23
	s_cselect_b32 s59, s7, s56
	s_cselect_b32 s58, s6, s55
	v_lshl_add_u64 v[154:155], s[20:21], 0, v[134:135]
	s_add_i32 m0, s31, 0xc000
	ds_read_b128 v[182:185], v139
	ds_read_b128 v[186:189], v139 offset:1024
	ds_read_b128 v[190:193], v139 offset:2048
	ds_read_b128 v[194:197], v139 offset:3072
	ds_read_b128 v[198:201], v139 offset:4096
	ds_read_b128 v[202:205], v139 offset:5120
	ds_read_b128 v[206:209], v139 offset:6144
	ds_read_b128 v[226:229], v139 offset:7168
	global_load_lds_dwordx4 v[154:155], off
	v_lshl_add_u64 v[154:155], s[20:21], 0, v[136:137]
	s_add_i32 m0, s31, 0xe000
	s_nop 0
	global_load_lds_dwordx4 v[154:155], off
	s_waitcnt vmcnt(8)
	s_waitcnt lgkmcnt(0)
	s_barrier
	s_waitcnt lgkmcnt(0)
	v_mfma_f32_16x16x32_bf16 v[120:123], v[142:145], v[182:185], v[120:123]
	v_mfma_f32_16x16x32_bf16 v[124:127], v[150:153], v[182:185], v[124:127]
	v_mfma_f32_16x16x32_bf16 v[108:111], v[142:145], v[190:193], v[108:111]
	v_mfma_f32_16x16x32_bf16 v[104:107], v[150:153], v[190:193], v[104:107]
	v_mfma_f32_16x16x32_bf16 v[92:95], v[142:145], v[198:201], v[92:95]
	v_mfma_f32_16x16x32_bf16 v[88:91], v[150:153], v[198:201], v[88:91]
	v_mfma_f32_16x16x32_bf16 v[76:79], v[142:145], v[206:209], v[76:79]
	v_mfma_f32_16x16x32_bf16 v[72:75], v[150:153], v[206:209], v[72:75]
	v_mfma_f32_16x16x32_bf16 v[120:123], v[146:149], v[186:189], v[120:123]
	v_mfma_f32_16x16x32_bf16 v[124:127], v[162:165], v[186:189], v[124:127]
	v_mfma_f32_16x16x32_bf16 v[108:111], v[146:149], v[194:197], v[108:111]
	v_mfma_f32_16x16x32_bf16 v[104:107], v[162:165], v[194:197], v[104:107]
	v_mfma_f32_16x16x32_bf16 v[92:95], v[146:149], v[202:205], v[92:95]
	v_mfma_f32_16x16x32_bf16 v[88:91], v[162:165], v[202:205], v[88:91]
	v_mfma_f32_16x16x32_bf16 v[76:79], v[146:149], v[226:229], v[76:79]
	v_mfma_f32_16x16x32_bf16 v[72:75], v[162:165], v[226:229], v[72:75]
	v_mfma_f32_16x16x32_bf16 v[116:119], v[166:169], v[182:185], v[116:119]
	v_mfma_f32_16x16x32_bf16 v[112:115], v[174:177], v[182:185], v[112:115]
	v_mfma_f32_16x16x32_bf16 v[100:103], v[166:169], v[190:193], v[100:103]
	v_mfma_f32_16x16x32_bf16 v[96:99], v[174:177], v[190:193], v[96:99]
	v_mfma_f32_16x16x32_bf16 v[84:87], v[166:169], v[198:201], v[84:87]
	v_mfma_f32_16x16x32_bf16 v[80:83], v[174:177], v[198:201], v[80:83]
	v_mfma_f32_16x16x32_bf16 v[68:71], v[166:169], v[206:209], v[68:71]
	v_mfma_f32_16x16x32_bf16 v[64:67], v[174:177], v[206:209], v[64:67]
	v_mfma_f32_16x16x32_bf16 v[116:119], v[170:173], v[186:189], v[116:119]
	v_mfma_f32_16x16x32_bf16 v[112:115], v[178:181], v[186:189], v[112:115]
	v_mfma_f32_16x16x32_bf16 v[100:103], v[170:173], v[194:197], v[100:103]
	v_mfma_f32_16x16x32_bf16 v[96:99], v[178:181], v[194:197], v[96:99]
	v_mfma_f32_16x16x32_bf16 v[84:87], v[170:173], v[202:205], v[84:87]
	v_mfma_f32_16x16x32_bf16 v[80:83], v[178:181], v[202:205], v[80:83]
	v_mfma_f32_16x16x32_bf16 v[68:71], v[170:173], v[226:229], v[68:71]
	v_mfma_f32_16x16x32_bf16 v[64:67], v[178:181], v[226:229], v[64:67]
	s_barrier
	s_mov_b32 m0, s34
	v_lshl_add_u64 v[154:155], s[58:59], 0, v[156:157]
	v_lshl_add_u64 v[210:211], s[58:59], 0, v[132:133]
	s_add_u32 s58, s58, s8
	ds_read_b128 v[182:185], v139 offset:16384
	ds_read_b128 v[186:189], v139 offset:17408
	ds_read_b128 v[190:193], v139 offset:18432
	ds_read_b128 v[194:197], v139 offset:19456
	ds_read_b128 v[198:201], v139 offset:20480
	ds_read_b128 v[202:205], v139 offset:21504
	ds_read_b128 v[206:209], v139 offset:22528
	ds_read_b128 v[226:229], v139 offset:23552
	global_load_lds_dwordx4 v[154:155], off
	s_mov_b32 m0, s35
	s_addc_u32 s59, s59, s9
	global_load_lds_dwordx4 v[210:211], off
	v_lshl_add_u64 v[216:217], s[58:59], 0, v[156:157]
	s_mov_b32 m0, s36
	v_lshl_add_u64 v[218:219], s[58:59], 0, v[132:133]
	global_load_lds_dwordx4 v[216:217], off
	s_mov_b32 m0, s37
	v_lshl_add_u64 v[220:221], s[22:23], 0, v[128:129]
	global_load_lds_dwordx4 v[218:219], off
	s_mov_b32 m0, s31
	v_lshl_add_u64 v[230:231], s[22:23], 0, v[130:131]
	global_load_lds_dwordx4 v[220:221], off
	s_mov_b32 m0, s38
	s_nop 0
	global_load_lds_dwordx4 v[230:231], off
	s_waitcnt vmcnt(8)
	s_waitcnt lgkmcnt(0)
	s_barrier
; #define PG8_STAGE(bufoff, gbase, voff) do { _Pragma("unroll") for (int _i = 0; _i < 2; ++_i) \
;         __builtin_amdgcn_global_load_lds((const unsigned*)((const char*)(gbase) + (voff)[_i]), (LAS unsigned*)(lds + (bufoff) + ldsw + _i * 8192), 16, 0, 0); } while (0)
; #define PG8_LDA(dst, b, h) do { _Pragma("unroll") for (int m = 0; m < 4; ++m) _Pragma("unroll") for (int k = 0; k < 2; ++k) dst[m][k] = *(const LAS bf16x8*)(lds + PG8_SA(b, h) + aoff + m * 2048 + k * 1024); } while (0)
; #define PG8_LDB(dst, b, h) do { _Pragma("unroll") for (int n = 0; n < 2; ++n) _Pragma("unroll") for (int k = 0; k < 2; ++k) dst[n][k] = *(const LAS bf16x8*)(lds + PG8_SB(b, h) + boff + n * 2048 + k * 1024); } while (0)
; #define PG8_MMA(ai, bj, At, Bt) do { __builtin_amdgcn_s_setprio(1); _Pragma("unroll") for (int m = 0; m < 4; ++m) _Pragma("unroll") for (int n = 0; n < 2; ++n) _Pragma("unroll") for (int k = 0; k < 2; ++k) \
;         acc[ai][bj][m][n] = __builtin_amdgcn_mfma_f32_16x16x32_bf16(Bt[n][k], At[m][k], acc[ai][bj][m][n], 0, 0, 0); __builtin_amdgcn_s_setprio(0); } while (0)
; #define PG8_WAIT_V(n) asm volatile("s_waitcnt vmcnt(" #n ")" ::: "memory")
; #define PG8_WAIT_L(n) asm volatile("s_waitcnt lgkmcnt(" #n ")" ::: "memory")
; #define PG8_BAR __builtin_amdgcn_s_barrier()
; #define PG8_SCHED __builtin_amdgcn_sched_barrier(0)
; template <class Epi>
; __device__ __forceinline__ void gemm_phase(LAS unsigned char* lds, const Gemm g, const StaticOrder& S, const Epi& E) {
;     ...
;             PG8_WAIT_V(8); PG8_WAIT_L(0); PG8_BAR; PG8_MMA(0, 0, At, B0); PG8_MMA(0, 1, At, B1); PG8_BAR; PG8_SCHED;
;             PG8_LDA(At, 0, 1); PG8_STAGE(PG8_SB(0, 0), b2, voffB); PG8_STAGE(PG8_SB(0, 1), b2 + hstep, voffB); PG8_STAGE(PG8_SA(0, 0), a2, voffA);
;             PG8_WAIT_V(8); PG8_WAIT_L(0); PG8_BAR; PG8_MMA(1, 0, At, B0); PG8_MMA(1, 1, At, B1); PG8_BAR; PG8_SCHED;
;             PG8_LDB(B0, 1, 0); PG8_LDB(B1, 1, 1); PG8_SCHED; PG8_LDA(At, 1, 0); PG8_STAGE(PG8_SA(0, 1), a2 + hstep, voffA);
;             PG8_WAIT_V(8); PG8_WAIT_L(0); PG8_BAR; PG8_MMA(0, 0, At, B0); PG8_MMA(0, 1, At, B1); PG8_BAR; PG8_SCHED;
;             PG8_LDA(At, 1, 1); PG8_STAGE(PG8_SB(1, 0), b3, voffB); PG8_STAGE(PG8_SB(1, 1), b3 + hstep, voffB); PG8_STAGE(PG8_SA(1, 0), a3, voffA);
;             PG8_WAIT_V(8); PG8_WAIT_L(0); PG8_BAR; PG8_MMA(1, 0, At, B0); PG8_MMA(1, 1, At, B1); PG8_BAR; PG8_SCHED;
	s_waitcnt lgkmcnt(0)
	v_mfma_f32_16x16x32_bf16 v[60:63], v[142:145], v[182:185], v[60:63]
	v_mfma_f32_16x16x32_bf16 v[56:59], v[150:153], v[182:185], v[56:59]
	v_mfma_f32_16x16x32_bf16 v[44:47], v[142:145], v[190:193], v[44:47]
	v_mfma_f32_16x16x32_bf16 v[40:43], v[150:153], v[190:193], v[40:43]
	v_mfma_f32_16x16x32_bf16 v[28:31], v[142:145], v[198:201], v[28:31]
	v_mfma_f32_16x16x32_bf16 v[24:27], v[150:153], v[198:201], v[24:27]
	v_mfma_f32_16x16x32_bf16 v[12:15], v[142:145], v[206:209], v[12:15]
	v_mfma_f32_16x16x32_bf16 v[8:11], v[150:153], v[206:209], v[8:11]
	v_mfma_f32_16x16x32_bf16 v[60:63], v[146:149], v[186:189], v[60:63]
	v_mfma_f32_16x16x32_bf16 v[56:59], v[162:165], v[186:189], v[56:59]
	v_mfma_f32_16x16x32_bf16 v[44:47], v[146:149], v[194:197], v[44:47]
	v_mfma_f32_16x16x32_bf16 v[40:43], v[162:165], v[194:197], v[40:43]
	v_mfma_f32_16x16x32_bf16 v[28:31], v[146:149], v[202:205], v[28:31]
	v_mfma_f32_16x16x32_bf16 v[24:27], v[162:165], v[202:205], v[24:27]
	v_mfma_f32_16x16x32_bf16 v[12:15], v[146:149], v[226:229], v[12:15]
	v_mfma_f32_16x16x32_bf16 v[8:11], v[162:165], v[226:229], v[8:11]
	v_mfma_f32_16x16x32_bf16 v[52:55], v[166:169], v[182:185], v[52:55]
	v_mfma_f32_16x16x32_bf16 v[48:51], v[174:177], v[182:185], v[48:51]
	v_mfma_f32_16x16x32_bf16 v[36:39], v[166:169], v[190:193], v[36:39]
	v_mfma_f32_16x16x32_bf16 v[32:35], v[174:177], v[190:193], v[32:35]
	v_mfma_f32_16x16x32_bf16 v[20:23], v[166:169], v[198:201], v[20:23]
	v_mfma_f32_16x16x32_bf16 v[16:19], v[174:177], v[198:201], v[16:19]
	v_mfma_f32_16x16x32_bf16 v[4:7], v[166:169], v[206:209], v[4:7]
	v_mfma_f32_16x16x32_bf16 v[0:3], v[174:177], v[206:209], v[0:3]
	v_mfma_f32_16x16x32_bf16 v[52:55], v[170:173], v[186:189], v[52:55]
	v_mfma_f32_16x16x32_bf16 v[48:51], v[178:181], v[186:189], v[48:51]
	v_mfma_f32_16x16x32_bf16 v[36:39], v[170:173], v[194:197], v[36:39]
	v_mfma_f32_16x16x32_bf16 v[32:35], v[178:181], v[194:197], v[32:35]
	v_mfma_f32_16x16x32_bf16 v[20:23], v[170:173], v[202:205], v[20:23]
	v_mfma_f32_16x16x32_bf16 v[16:19], v[178:181], v[202:205], v[16:19]
	v_mfma_f32_16x16x32_bf16 v[4:7], v[170:173], v[226:229], v[4:7]
	v_mfma_f32_16x16x32_bf16 v[0:3], v[178:181], v[226:229], v[0:3]
	s_barrier
	v_or_b32_e32 v142, 0x18000, v140
	v_add_u32_e32 v146, 0x18400, v140
	v_add_u32_e32 v150, 0x18800, v140
	v_add_u32_e32 v162, 0x18c00, v140
	v_or_b32_e32 v166, 0x1c000, v140
	v_add_u32_e32 v170, 0x1c400, v140
	v_add_u32_e32 v174, 0x1c800, v140
	v_add_u32_e32 v178, 0x1cc00, v140
	ds_read_b128 v[142:145], v142
	ds_read_b128 v[146:149], v146
	ds_read_b128 v[150:153], v150
	ds_read_b128 v[162:165], v162
	ds_read_b128 v[166:169], v166
	ds_read_b128 v[170:173], v170
	ds_read_b128 v[174:177], v174
	ds_read_b128 v[178:181], v178
	s_add_u32 s22, s22, s8
	s_addc_u32 s23, s23, s9
	s_mov_b32 m0, s39
	v_lshl_add_u64 v[232:233], s[22:23], 0, v[128:129]
	ds_read_b128 v[182:185], v139 offset:32768
	ds_read_b128 v[186:189], v139 offset:33792
	ds_read_b128 v[190:193], v139 offset:34816
	ds_read_b128 v[194:197], v139 offset:35840
	ds_read_b128 v[198:201], v139 offset:36864
	ds_read_b128 v[202:205], v139 offset:37888
	ds_read_b128 v[206:209], v139 offset:38912
	ds_read_b128 v[226:229], v139 offset:39936
	global_load_lds_dwordx4 v[232:233], off
	v_lshl_add_u64 v[232:233], s[22:23], 0, v[130:131]
	s_mov_b32 m0, s40
	s_nop 0
	global_load_lds_dwordx4 v[232:233], off
	s_waitcnt vmcnt(8)
	s_waitcnt lgkmcnt(0)
	s_barrier
	s_waitcnt lgkmcnt(0)
	v_mfma_f32_16x16x32_bf16 v[120:123], v[142:145], v[182:185], v[120:123]
	v_mfma_f32_16x16x32_bf16 v[124:127], v[150:153], v[182:185], v[124:127]
	v_mfma_f32_16x16x32_bf16 v[108:111], v[142:145], v[190:193], v[108:111]
	v_mfma_f32_16x16x32_bf16 v[104:107], v[150:153], v[190:193], v[104:107]
	v_mfma_f32_16x16x32_bf16 v[92:95], v[142:145], v[198:201], v[92:95]
	v_mfma_f32_16x16x32_bf16 v[88:91], v[150:153], v[198:201], v[88:91]
	v_mfma_f32_16x16x32_bf16 v[76:79], v[142:145], v[206:209], v[76:79]
	v_mfma_f32_16x16x32_bf16 v[72:75], v[150:153], v[206:209], v[72:75]
	v_mfma_f32_16x16x32_bf16 v[120:123], v[146:149], v[186:189], v[120:123]
	v_mfma_f32_16x16x32_bf16 v[124:127], v[162:165], v[186:189], v[124:127]
	v_mfma_f32_16x16x32_bf16 v[108:111], v[146:149], v[194:197], v[108:111]
	v_mfma_f32_16x16x32_bf16 v[104:107], v[162:165], v[194:197], v[104:107]
	v_mfma_f32_16x16x32_bf16 v[92:95], v[146:149], v[202:205], v[92:95]
	v_mfma_f32_16x16x32_bf16 v[88:91], v[162:165], v[202:205], v[88:91]
	v_mfma_f32_16x16x32_bf16 v[76:79], v[146:149], v[226:229], v[76:79]
	v_mfma_f32_16x16x32_bf16 v[72:75], v[162:165], v[226:229], v[72:75]
	v_mfma_f32_16x16x32_bf16 v[116:119], v[166:169], v[182:185], v[116:119]
	v_mfma_f32_16x16x32_bf16 v[112:115], v[174:177], v[182:185], v[112:115]
	v_mfma_f32_16x16x32_bf16 v[100:103], v[166:169], v[190:193], v[100:103]
	v_mfma_f32_16x16x32_bf16 v[96:99], v[174:177], v[190:193], v[96:99]
	v_mfma_f32_16x16x32_bf16 v[84:87], v[166:169], v[198:201], v[84:87]
	v_mfma_f32_16x16x32_bf16 v[80:83], v[174:177], v[198:201], v[80:83]
	v_mfma_f32_16x16x32_bf16 v[68:71], v[166:169], v[206:209], v[68:71]
	v_mfma_f32_16x16x32_bf16 v[64:67], v[174:177], v[206:209], v[64:67]
	v_mfma_f32_16x16x32_bf16 v[116:119], v[170:173], v[186:189], v[116:119]
	v_mfma_f32_16x16x32_bf16 v[112:115], v[178:181], v[186:189], v[112:115]
	v_mfma_f32_16x16x32_bf16 v[100:103], v[170:173], v[194:197], v[100:103]
	v_mfma_f32_16x16x32_bf16 v[96:99], v[178:181], v[194:197], v[96:99]
	v_mfma_f32_16x16x32_bf16 v[84:87], v[170:173], v[202:205], v[84:87]
	v_mfma_f32_16x16x32_bf16 v[80:83], v[178:181], v[202:205], v[80:83]
	v_mfma_f32_16x16x32_bf16 v[68:71], v[170:173], v[226:229], v[68:71]
	v_mfma_f32_16x16x32_bf16 v[64:67], v[178:181], v[226:229], v[64:67]
	s_barrier
; #define PG8_STAGE(bufoff, gbase, voff) do { _Pragma("unroll") for (int _i = 0; _i < 2; ++_i) \
;         __builtin_amdgcn_global_load_lds((const unsigned*)((const char*)(gbase) + (voff)[_i]), (LAS unsigned*)(lds + (bufoff) + ldsw + _i * 8192), 16, 0, 0); } while (0)
; #define PG8_LDA(dst, b, h) do { _Pragma("unroll") for (int m = 0; m < 4; ++m) _Pragma("unroll") for (int k = 0; k < 2; ++k) dst[m][k] = *(const LAS bf16x8*)(lds + PG8_SA(b, h) + aoff + m * 2048 + k * 1024); } while (0)
; #define PG8_MMA(ai, bj, At, Bt) do { __builtin_amdgcn_s_setprio(1); _Pragma("unroll") for (int m = 0; m < 4; ++m) _Pragma("unroll") for (int n = 0; n < 2; ++n) _Pragma("unroll") for (int k = 0; k < 2; ++k) \
;         acc[ai][bj][m][n] = __builtin_amdgcn_mfma_f32_16x16x32_bf16(Bt[n][k], At[m][k], acc[ai][bj][m][n], 0, 0, 0); __builtin_amdgcn_s_setprio(0); } while (0)
; #define PG8_WAIT_V(n) asm volatile("s_waitcnt vmcnt(" #n ")" ::: "memory")
; #define PG8_WAIT_L(n) asm volatile("s_waitcnt lgkmcnt(" #n ")" ::: "memory")
; #define PG8_BAR __builtin_amdgcn_s_barrier()
; #define PG8_SCHED __builtin_amdgcn_sched_barrier(0)
; template <class Epi>
; __device__ __forceinline__ void gemm_phase(LAS unsigned char* lds, const Gemm g, const StaticOrder& S, const Epi& E) {
;     ...
;             PG8_LDA(At, 1, 1); PG8_STAGE(PG8_SB(1, 0), b3, voffB); PG8_STAGE(PG8_SB(1, 1), b3 + hstep, voffB); PG8_STAGE(PG8_SA(1, 0), a3, voffA);
;             PG8_WAIT_V(8); PG8_WAIT_L(0); PG8_BAR; PG8_MMA(1, 0, At, B0); PG8_MMA(1, 1, At, B1); PG8_BAR; PG8_SCHED;
;         }
	s_mov_b32 m0, s41
	v_lshl_add_u64 v[154:155], v[154:155], 0, s[82:83]
	ds_read_b128 v[182:185], v139 offset:49152
	ds_read_b128 v[186:189], v139 offset:50176
	ds_read_b128 v[190:193], v139 offset:51200
	ds_read_b128 v[194:197], v139 offset:52224
	ds_read_b128 v[198:201], v139 offset:53248
	ds_read_b128 v[202:205], v139 offset:54272
	ds_read_b128 v[206:209], v139 offset:55296
	ds_read_b128 v[226:229], v139 offset:56320
	global_load_lds_dwordx4 v[154:155], off
	v_lshl_add_u64 v[154:155], v[210:211], 0, s[82:83]
	s_mov_b32 m0, s42
	s_nop 0
	global_load_lds_dwordx4 v[154:155], off
	v_lshl_add_u64 v[154:155], v[216:217], 0, s[82:83]
	s_mov_b32 m0, s45
	s_nop 0
	global_load_lds_dwordx4 v[154:155], off
	v_lshl_add_u64 v[154:155], v[218:219], 0, s[82:83]
	s_mov_b32 m0, s46
	s_nop 0
	global_load_lds_dwordx4 v[154:155], off
	v_lshl_add_u64 v[154:155], v[220:221], 0, s[82:83]
	s_mov_b32 m0, s43
	s_nop 0
	global_load_lds_dwordx4 v[154:155], off
	v_lshl_add_u64 v[154:155], v[230:231], 0, s[82:83]
	s_mov_b32 m0, s44
	s_nop 0
	global_load_lds_dwordx4 v[154:155], off
	s_waitcnt vmcnt(8)
	s_waitcnt lgkmcnt(0)
	s_barrier
	s_waitcnt lgkmcnt(0)
	v_mfma_f32_16x16x32_bf16 v[60:63], v[142:145], v[182:185], v[60:63]
	v_mfma_f32_16x16x32_bf16 v[56:59], v[150:153], v[182:185], v[56:59]
	v_mfma_f32_16x16x32_bf16 v[44:47], v[142:145], v[190:193], v[44:47]
	v_mfma_f32_16x16x32_bf16 v[40:43], v[150:153], v[190:193], v[40:43]
	v_mfma_f32_16x16x32_bf16 v[28:31], v[142:145], v[198:201], v[28:31]
	v_mfma_f32_16x16x32_bf16 v[24:27], v[150:153], v[198:201], v[24:27]
	v_mfma_f32_16x16x32_bf16 v[12:15], v[142:145], v[206:209], v[12:15]
	v_mfma_f32_16x16x32_bf16 v[8:11], v[150:153], v[206:209], v[8:11]
	v_mfma_f32_16x16x32_bf16 v[60:63], v[146:149], v[186:189], v[60:63]
	v_mfma_f32_16x16x32_bf16 v[56:59], v[162:165], v[186:189], v[56:59]
	v_mfma_f32_16x16x32_bf16 v[44:47], v[146:149], v[194:197], v[44:47]
	v_mfma_f32_16x16x32_bf16 v[40:43], v[162:165], v[194:197], v[40:43]
	v_mfma_f32_16x16x32_bf16 v[28:31], v[146:149], v[202:205], v[28:31]
	v_mfma_f32_16x16x32_bf16 v[24:27], v[162:165], v[202:205], v[24:27]
	v_mfma_f32_16x16x32_bf16 v[12:15], v[146:149], v[226:229], v[12:15]
	v_mfma_f32_16x16x32_bf16 v[8:11], v[162:165], v[226:229], v[8:11]
	v_mfma_f32_16x16x32_bf16 v[52:55], v[166:169], v[182:185], v[52:55]
	v_mfma_f32_16x16x32_bf16 v[48:51], v[174:177], v[182:185], v[48:51]
	v_mfma_f32_16x16x32_bf16 v[36:39], v[166:169], v[190:193], v[36:39]
	v_mfma_f32_16x16x32_bf16 v[32:35], v[174:177], v[190:193], v[32:35]
	v_mfma_f32_16x16x32_bf16 v[20:23], v[166:169], v[198:201], v[20:23]
	v_mfma_f32_16x16x32_bf16 v[16:19], v[174:177], v[198:201], v[16:19]
	v_mfma_f32_16x16x32_bf16 v[4:7], v[166:169], v[206:209], v[4:7]
	v_mfma_f32_16x16x32_bf16 v[0:3], v[174:177], v[206:209], v[0:3]
	v_mfma_f32_16x16x32_bf16 v[52:55], v[170:173], v[186:189], v[52:55]
	v_mfma_f32_16x16x32_bf16 v[48:51], v[178:181], v[186:189], v[48:51]
	v_mfma_f32_16x16x32_bf16 v[36:39], v[170:173], v[194:197], v[36:39]
	v_mfma_f32_16x16x32_bf16 v[32:35], v[178:181], v[194:197], v[32:35]
	v_mfma_f32_16x16x32_bf16 v[20:23], v[170:173], v[202:205], v[20:23]
	v_mfma_f32_16x16x32_bf16 v[16:19], v[178:181], v[202:205], v[16:19]
	v_mfma_f32_16x16x32_bf16 v[4:7], v[170:173], v[226:229], v[4:7]
	v_mfma_f32_16x16x32_bf16 v[0:3], v[178:181], v[226:229], v[0:3]
	s_barrier
	s_add_u32 s20, s20, 0x100
	s_addc_u32 s21, s21, 0
	s_add_u32 s55, s55, 0x100
	s_addc_u32 s56, s56, 0
	s_cmp_ge_i32 s57, s47
	s_mov_b32 s22, s57
	s_cbranch_scc0 .LBB0_768

; #define PG8_STAGE(bufoff, gbase, voff) do { _Pragma("unroll") for (int _i = 0; _i < 2; ++_i) \
;         __builtin_amdgcn_global_load_lds((const unsigned*)((const char*)(gbase) + (voff)[_i]), (LAS unsigned*)(lds + (bufoff) + ldsw + _i * 8192), 16, 0, 0); } while (0)
; #define PG8_LDA(dst, b, h) do { _Pragma("unroll") for (int m = 0; m < 4; ++m) _Pragma("unroll") for (int k = 0; k < 2; ++k) dst[m][k] = *(const LAS bf16x8*)(lds + PG8_SA(b, h) + aoff + m * 2048 + k * 1024); } while (0)
; #define PG8_LDB(dst, b, h) do { _Pragma("unroll") for (int n = 0; n < 2; ++n) _Pragma("unroll") for (int k = 0; k < 2; ++k) dst[n][k] = *(const LAS bf16x8*)(lds + PG8_SB(b, h) + boff + n * 2048 + k * 1024); } while (0)
; #define PG8_MMA(ai, bj, At, Bt) do { __builtin_amdgcn_s_setprio(1); _Pragma("unroll") for (int m = 0; m < 4; ++m) _Pragma("unroll") for (int n = 0; n < 2; ++n) _Pragma("unroll") for (int k = 0; k < 2; ++k) \
;         acc[ai][bj][m][n] = __builtin_amdgcn_mfma_f32_16x16x32_bf16(Bt[n][k], At[m][k], acc[ai][bj][m][n], 0, 0, 0); __builtin_amdgcn_s_setprio(0); } while (0)
; #define PG8_WAIT_V(n) asm volatile("s_waitcnt vmcnt(" #n ")" ::: "memory")
; #define PG8_WAIT_L(n) asm volatile("s_waitcnt lgkmcnt(" #n ")" ::: "memory")
; #define PG8_BAR __builtin_amdgcn_s_barrier()
; #define PG8_SCHED __builtin_amdgcn_sched_barrier(0)
; template <class Epi>
; __device__ __forceinline__ void gemm_phase(LAS unsigned char* lds, const Gemm g, const StaticOrder& S, const Epi& E) {
;     ...
;             const bool last = (t == nt - 2);
;             const char* a1 = cA + (size_t)(t + 1) * kstep;
;             const char* a2 = last ? nA : cA + (size_t)(t + 2) * kstep; const char* b2 = last ? nB : cB + (size_t)(t + 2) * kstep;
;             const char* a3 = a2 + kstep; const char* b3 = b2 + kstep;
;             if (last && has_next) E.prep(nxt, (ui + 1) & 1, rsl, tid);
;             PG8_LDB(B0, 0, 0); PG8_LDB(B1, 0, 1); PG8_SCHED; PG8_LDA(At, 0, 0); PG8_STAGE(PG8_SA(1, 1), a1 + hstep, voffA);
;             PG8_WAIT_V(8); PG8_WAIT_L(0); PG8_BAR; PG8_MMA(0, 0, At, B0); PG8_MMA(0, 1, At, B1); PG8_BAR; PG8_SCHED;
;             PG8_LDA(At, 0, 1); PG8_STAGE(PG8_SB(0, 0), b2, voffB); PG8_STAGE(PG8_SB(0, 1), b2 + hstep, voffB); PG8_STAGE(PG8_SA(0, 0), a2, voffA);
;             PG8_WAIT_V(8); PG8_WAIT_L(0); PG8_BAR; PG8_MMA(1, 0, At, B0); PG8_MMA(1, 1, At, B1); PG8_BAR; PG8_SCHED;
.LBB0_799:
	v_or_b32_e32 v142, 0x10000, v140
	v_add_u32_e32 v146, 0x10400, v140
	v_add_u32_e32 v150, 0x10800, v140
	v_add_u32_e32 v154, 0x10c00, v140
	ds_read_b128 v[142:145], v142
	ds_read_b128 v[146:149], v146
	ds_read_b128 v[150:153], v150
	ds_read_b128 v[162:165], v154
	v_or_b32_e32 v154, 0x14000, v140
	v_add_u32_e32 v155, 0x14400, v140
	ds_read_b128 v[166:169], v154
	ds_read_b128 v[170:173], v155
	v_add_u32_e32 v154, 0x14800, v140
	s_add_i32 s53, s20, 2
	v_add_u32_e32 v155, 0x14c00, v140
	ds_read_b128 v[174:177], v154
	ds_read_b128 v[178:181], v155
	s_add_u32 s54, s18, 0x80
	s_addc_u32 s21, s19, 0
	s_cmp_eq_u32 s47, s20
	s_cselect_b32 s20, s0, s54
	s_cselect_b32 s21, s1, s21
	s_cselect_b32 s55, s7, s52
	s_cselect_b32 s54, s6, s51
	v_lshl_add_u64 v[154:155], s[18:19], 0, v[134:135]
	s_add_i32 m0, s28, 0xc000
	ds_read_b128 v[182:185], v139
	ds_read_b128 v[186:189], v139 offset:1024
	ds_read_b128 v[190:193], v139 offset:2048
	ds_read_b128 v[194:197], v139 offset:3072
	ds_read_b128 v[198:201], v139 offset:4096
	ds_read_b128 v[202:205], v139 offset:5120
	ds_read_b128 v[206:209], v139 offset:6144
	ds_read_b128 v[226:229], v139 offset:7168
	global_load_lds_dwordx4 v[154:155], off
	v_lshl_add_u64 v[154:155], s[18:19], 0, v[136:137]
	s_add_i32 m0, s28, 0xe000
	s_nop 0
	global_load_lds_dwordx4 v[154:155], off
	s_waitcnt vmcnt(8)
	s_waitcnt lgkmcnt(0)
	s_barrier
	s_waitcnt lgkmcnt(0)
	v_mfma_f32_16x16x32_bf16 v[120:123], v[142:145], v[182:185], v[120:123]
	v_mfma_f32_16x16x32_bf16 v[124:127], v[150:153], v[182:185], v[124:127]
	v_mfma_f32_16x16x32_bf16 v[108:111], v[142:145], v[190:193], v[108:111]
	v_mfma_f32_16x16x32_bf16 v[104:107], v[150:153], v[190:193], v[104:107]
	v_mfma_f32_16x16x32_bf16 v[92:95], v[142:145], v[198:201], v[92:95]
	v_mfma_f32_16x16x32_bf16 v[88:91], v[150:153], v[198:201], v[88:91]
	v_mfma_f32_16x16x32_bf16 v[76:79], v[142:145], v[206:209], v[76:79]
	v_mfma_f32_16x16x32_bf16 v[72:75], v[150:153], v[206:209], v[72:75]
	v_mfma_f32_16x16x32_bf16 v[120:123], v[146:149], v[186:189], v[120:123]
	v_mfma_f32_16x16x32_bf16 v[124:127], v[162:165], v[186:189], v[124:127]
	v_mfma_f32_16x16x32_bf16 v[108:111], v[146:149], v[194:197], v[108:111]
	v_mfma_f32_16x16x32_bf16 v[104:107], v[162:165], v[194:197], v[104:107]
	v_mfma_f32_16x16x32_bf16 v[92:95], v[146:149], v[202:205], v[92:95]
	v_mfma_f32_16x16x32_bf16 v[88:91], v[162:165], v[202:205], v[88:91]
	v_mfma_f32_16x16x32_bf16 v[76:79], v[146:149], v[226:229], v[76:79]
	v_mfma_f32_16x16x32_bf16 v[72:75], v[162:165], v[226:229], v[72:75]
	v_mfma_f32_16x16x32_bf16 v[116:119], v[166:169], v[182:185], v[116:119]
	v_mfma_f32_16x16x32_bf16 v[112:115], v[174:177], v[182:185], v[112:115]
	v_mfma_f32_16x16x32_bf16 v[100:103], v[166:169], v[190:193], v[100:103]
	v_mfma_f32_16x16x32_bf16 v[96:99], v[174:177], v[190:193], v[96:99]
	v_mfma_f32_16x16x32_bf16 v[84:87], v[166:169], v[198:201], v[84:87]
	v_mfma_f32_16x16x32_bf16 v[80:83], v[174:177], v[198:201], v[80:83]
	v_mfma_f32_16x16x32_bf16 v[68:71], v[166:169], v[206:209], v[68:71]
	v_mfma_f32_16x16x32_bf16 v[64:67], v[174:177], v[206:209], v[64:67]
	v_mfma_f32_16x16x32_bf16 v[116:119], v[170:173], v[186:189], v[116:119]
	v_mfma_f32_16x16x32_bf16 v[112:115], v[178:181], v[186:189], v[112:115]
	v_mfma_f32_16x16x32_bf16 v[100:103], v[170:173], v[194:197], v[100:103]
	v_mfma_f32_16x16x32_bf16 v[96:99], v[178:181], v[194:197], v[96:99]
	v_mfma_f32_16x16x32_bf16 v[84:87], v[170:173], v[202:205], v[84:87]
	v_mfma_f32_16x16x32_bf16 v[80:83], v[178:181], v[202:205], v[80:83]
	v_mfma_f32_16x16x32_bf16 v[68:71], v[170:173], v[226:229], v[68:71]
	v_mfma_f32_16x16x32_bf16 v[64:67], v[178:181], v[226:229], v[64:67]
	s_barrier
	s_mov_b32 m0, s29
	v_lshl_add_u64 v[154:155], s[54:55], 0, v[156:157]
	v_lshl_add_u64 v[210:211], s[54:55], 0, v[132:133]
	s_add_u32 s54, s54, s2
	ds_read_b128 v[182:185], v139 offset:16384
	ds_read_b128 v[186:189], v139 offset:17408
	ds_read_b128 v[190:193], v139 offset:18432
	ds_read_b128 v[194:197], v139 offset:19456
	ds_read_b128 v[198:201], v139 offset:20480
	ds_read_b128 v[202:205], v139 offset:21504
	ds_read_b128 v[206:209], v139 offset:22528
	ds_read_b128 v[226:229], v139 offset:23552
	global_load_lds_dwordx4 v[154:155], off
	s_mov_b32 m0, s30
	s_addc_u32 s55, s55, s3
	global_load_lds_dwordx4 v[210:211], off
	v_lshl_add_u64 v[216:217], s[54:55], 0, v[156:157]
	s_mov_b32 m0, s31
	v_lshl_add_u64 v[218:219], s[54:55], 0, v[132:133]
	global_load_lds_dwordx4 v[216:217], off
	s_mov_b32 m0, s34
	v_lshl_add_u64 v[220:221], s[20:21], 0, v[128:129]
	global_load_lds_dwordx4 v[218:219], off
	s_mov_b32 m0, s28
	v_lshl_add_u64 v[230:231], s[20:21], 0, v[130:131]
	global_load_lds_dwordx4 v[220:221], off
	s_mov_b32 m0, s35
	s_nop 0
	global_load_lds_dwordx4 v[230:231], off
	s_waitcnt vmcnt(8)
	s_waitcnt lgkmcnt(0)
	s_barrier
; #define PG8_STAGE(bufoff, gbase, voff) do { _Pragma("unroll") for (int _i = 0; _i < 2; ++_i) \
;         __builtin_amdgcn_global_load_lds((const unsigned*)((const char*)(gbase) + (voff)[_i]), (LAS unsigned*)(lds + (bufoff) + ldsw + _i * 8192), 16, 0, 0); } while (0)
; #define PG8_LDA(dst, b, h) do { _Pragma("unroll") for (int m = 0; m < 4; ++m) _Pragma("unroll") for (int k = 0; k < 2; ++k) dst[m][k] = *(const LAS bf16x8*)(lds + PG8_SA(b, h) + aoff + m * 2048 + k * 1024); } while (0)
; #define PG8_LDB(dst, b, h) do { _Pragma("unroll") for (int n = 0; n < 2; ++n) _Pragma("unroll") for (int k = 0; k < 2; ++k) dst[n][k] = *(const LAS bf16x8*)(lds + PG8_SB(b, h) + boff + n * 2048 + k * 1024); } while (0)
; #define PG8_MMA(ai, bj, At, Bt) do { __builtin_amdgcn_s_setprio(1); _Pragma("unroll") for (int m = 0; m < 4; ++m) _Pragma("unroll") for (int n = 0; n < 2; ++n) _Pragma("unroll") for (int k = 0; k < 2; ++k) \
;         acc[ai][bj][m][n] = __builtin_amdgcn_mfma_f32_16x16x32_bf16(Bt[n][k], At[m][k], acc[ai][bj][m][n], 0, 0, 0); __builtin_amdgcn_s_setprio(0); } while (0)
; #define PG8_WAIT_V(n) asm volatile("s_waitcnt vmcnt(" #n ")" ::: "memory")
; #define PG8_WAIT_L(n) asm volatile("s_waitcnt lgkmcnt(" #n ")" ::: "memory")
; #define PG8_BAR __builtin_amdgcn_s_barrier()
; #define PG8_SCHED __builtin_amdgcn_sched_barrier(0)
; template <class Epi>
; __device__ __forceinline__ void gemm_phase(LAS unsigned char* lds, const Gemm g, const StaticOrder& S, const Epi& E) {
;     ...
;             PG8_WAIT_V(8); PG8_WAIT_L(0); PG8_BAR; PG8_MMA(1, 0, At, B0); PG8_MMA(1, 1, At, B1); PG8_BAR; PG8_SCHED;
;             PG8_LDB(B0, 1, 0); PG8_LDB(B1, 1, 1); PG8_SCHED; PG8_LDA(At, 1, 0); PG8_STAGE(PG8_SA(0, 1), a2 + hstep, voffA);
;             PG8_WAIT_V(8); PG8_WAIT_L(0); PG8_BAR; PG8_MMA(0, 0, At, B0); PG8_MMA(0, 1, At, B1); PG8_BAR; PG8_SCHED;
	s_waitcnt lgkmcnt(0)
	v_mfma_f32_16x16x32_bf16 v[60:63], v[142:145], v[182:185], v[60:63]
	v_mfma_f32_16x16x32_bf16 v[56:59], v[150:153], v[182:185], v[56:59]
	v_mfma_f32_16x16x32_bf16 v[44:47], v[142:145], v[190:193], v[44:47]
	v_mfma_f32_16x16x32_bf16 v[40:43], v[150:153], v[190:193], v[40:43]
	v_mfma_f32_16x16x32_bf16 v[28:31], v[142:145], v[198:201], v[28:31]
	v_mfma_f32_16x16x32_bf16 v[24:27], v[150:153], v[198:201], v[24:27]
	v_mfma_f32_16x16x32_bf16 v[12:15], v[142:145], v[206:209], v[12:15]
	v_mfma_f32_16x16x32_bf16 v[8:11], v[150:153], v[206:209], v[8:11]
	v_mfma_f32_16x16x32_bf16 v[60:63], v[146:149], v[186:189], v[60:63]
	v_mfma_f32_16x16x32_bf16 v[56:59], v[162:165], v[186:189], v[56:59]
	v_mfma_f32_16x16x32_bf16 v[44:47], v[146:149], v[194:197], v[44:47]
	v_mfma_f32_16x16x32_bf16 v[40:43], v[162:165], v[194:197], v[40:43]
	v_mfma_f32_16x16x32_bf16 v[28:31], v[146:149], v[202:205], v[28:31]
	v_mfma_f32_16x16x32_bf16 v[24:27], v[162:165], v[202:205], v[24:27]
	v_mfma_f32_16x16x32_bf16 v[12:15], v[146:149], v[226:229], v[12:15]
	v_mfma_f32_16x16x32_bf16 v[8:11], v[162:165], v[226:229], v[8:11]
	v_mfma_f32_16x16x32_bf16 v[52:55], v[166:169], v[182:185], v[52:55]
	v_mfma_f32_16x16x32_bf16 v[48:51], v[174:177], v[182:185], v[48:51]
	v_mfma_f32_16x16x32_bf16 v[36:39], v[166:169], v[190:193], v[36:39]
	v_mfma_f32_16x16x32_bf16 v[32:35], v[174:177], v[190:193], v[32:35]
	v_mfma_f32_16x16x32_bf16 v[20:23], v[166:169], v[198:201], v[20:23]
	v_mfma_f32_16x16x32_bf16 v[16:19], v[174:177], v[198:201], v[16:19]
	v_mfma_f32_16x16x32_bf16 v[4:7], v[166:169], v[206:209], v[4:7]
	v_mfma_f32_16x16x32_bf16 v[0:3], v[174:177], v[206:209], v[0:3]
	v_mfma_f32_16x16x32_bf16 v[52:55], v[170:173], v[186:189], v[52:55]
	v_mfma_f32_16x16x32_bf16 v[48:51], v[178:181], v[186:189], v[48:51]
	v_mfma_f32_16x16x32_bf16 v[36:39], v[170:173], v[194:197], v[36:39]
	v_mfma_f32_16x16x32_bf16 v[32:35], v[178:181], v[194:197], v[32:35]
	v_mfma_f32_16x16x32_bf16 v[20:23], v[170:173], v[202:205], v[20:23]
	v_mfma_f32_16x16x32_bf16 v[16:19], v[178:181], v[202:205], v[16:19]
	v_mfma_f32_16x16x32_bf16 v[4:7], v[170:173], v[226:229], v[4:7]
	v_mfma_f32_16x16x32_bf16 v[0:3], v[178:181], v[226:229], v[0:3]
	s_barrier
	v_or_b32_e32 v142, 0x18000, v140
	v_add_u32_e32 v146, 0x18400, v140
	v_add_u32_e32 v150, 0x18800, v140
	v_add_u32_e32 v162, 0x18c00, v140
	v_or_b32_e32 v166, 0x1c000, v140
	v_add_u32_e32 v170, 0x1c400, v140
	v_add_u32_e32 v174, 0x1c800, v140
	v_add_u32_e32 v178, 0x1cc00, v140
	ds_read_b128 v[142:145], v142
	ds_read_b128 v[146:149], v146
	ds_read_b128 v[150:153], v150
	ds_read_b128 v[162:165], v162
	ds_read_b128 v[166:169], v166
	ds_read_b128 v[170:173], v170
	ds_read_b128 v[174:177], v174
	ds_read_b128 v[178:181], v178
	s_add_u32 s20, s20, s2
	s_addc_u32 s21, s21, s3
	s_mov_b32 m0, s36
	v_lshl_add_u64 v[232:233], s[20:21], 0, v[128:129]
	ds_read_b128 v[182:185], v139 offset:32768
	ds_read_b128 v[186:189], v139 offset:33792
	ds_read_b128 v[190:193], v139 offset:34816
	ds_read_b128 v[194:197], v139 offset:35840
	ds_read_b128 v[198:201], v139 offset:36864
	ds_read_b128 v[202:205], v139 offset:37888
	ds_read_b128 v[206:209], v139 offset:38912
	ds_read_b128 v[226:229], v139 offset:39936
	global_load_lds_dwordx4 v[232:233], off
	v_lshl_add_u64 v[232:233], s[20:21], 0, v[130:131]
	s_mov_b32 m0, s37
	s_nop 0
	global_load_lds_dwordx4 v[232:233], off
	s_waitcnt vmcnt(8)
	s_waitcnt lgkmcnt(0)
	s_barrier
	s_waitcnt lgkmcnt(0)
	v_mfma_f32_16x16x32_bf16 v[120:123], v[142:145], v[182:185], v[120:123]
	v_mfma_f32_16x16x32_bf16 v[124:127], v[150:153], v[182:185], v[124:127]
	v_mfma_f32_16x16x32_bf16 v[108:111], v[142:145], v[190:193], v[108:111]
	v_mfma_f32_16x16x32_bf16 v[104:107], v[150:153], v[190:193], v[104:107]
	v_mfma_f32_16x16x32_bf16 v[92:95], v[142:145], v[198:201], v[92:95]
	v_mfma_f32_16x16x32_bf16 v[88:91], v[150:153], v[198:201], v[88:91]
	v_mfma_f32_16x16x32_bf16 v[76:79], v[142:145], v[206:209], v[76:79]
	v_mfma_f32_16x16x32_bf16 v[72:75], v[150:153], v[206:209], v[72:75]
	v_mfma_f32_16x16x32_bf16 v[120:123], v[146:149], v[186:189], v[120:123]
	v_mfma_f32_16x16x32_bf16 v[124:127], v[162:165], v[186:189], v[124:127]
	v_mfma_f32_16x16x32_bf16 v[108:111], v[146:149], v[194:197], v[108:111]
	v_mfma_f32_16x16x32_bf16 v[104:107], v[162:165], v[194:197], v[104:107]
	v_mfma_f32_16x16x32_bf16 v[92:95], v[146:149], v[202:205], v[92:95]
	v_mfma_f32_16x16x32_bf16 v[88:91], v[162:165], v[202:205], v[88:91]
	v_mfma_f32_16x16x32_bf16 v[76:79], v[146:149], v[226:229], v[76:79]
	v_mfma_f32_16x16x32_bf16 v[72:75], v[162:165], v[226:229], v[72:75]
	v_mfma_f32_16x16x32_bf16 v[116:119], v[166:169], v[182:185], v[116:119]
	v_mfma_f32_16x16x32_bf16 v[112:115], v[174:177], v[182:185], v[112:115]
	v_mfma_f32_16x16x32_bf16 v[100:103], v[166:169], v[190:193], v[100:103]
	v_mfma_f32_16x16x32_bf16 v[96:99], v[174:177], v[190:193], v[96:99]
	v_mfma_f32_16x16x32_bf16 v[84:87], v[166:169], v[198:201], v[84:87]
	v_mfma_f32_16x16x32_bf16 v[80:83], v[174:177], v[198:201], v[80:83]
	v_mfma_f32_16x16x32_bf16 v[68:71], v[166:169], v[206:209], v[68:71]
	v_mfma_f32_16x16x32_bf16 v[64:67], v[174:177], v[206:209], v[64:67]
	v_mfma_f32_16x16x32_bf16 v[116:119], v[170:173], v[186:189], v[116:119]
	v_mfma_f32_16x16x32_bf16 v[112:115], v[178:181], v[186:189], v[112:115]
	v_mfma_f32_16x16x32_bf16 v[100:103], v[170:173], v[194:197], v[100:103]
	v_mfma_f32_16x16x32_bf16 v[96:99], v[178:181], v[194:197], v[96:99]
	v_mfma_f32_16x16x32_bf16 v[84:87], v[170:173], v[202:205], v[84:87]
	v_mfma_f32_16x16x32_bf16 v[80:83], v[178:181], v[202:205], v[80:83]
	v_mfma_f32_16x16x32_bf16 v[68:71], v[170:173], v[226:229], v[68:71]
	v_mfma_f32_16x16x32_bf16 v[64:67], v[178:181], v[226:229], v[64:67]
	s_barrier
; #define PG8_STAGE(bufoff, gbase, voff) do { _Pragma("unroll") for (int _i = 0; _i < 2; ++_i) \
;         __builtin_amdgcn_global_load_lds((const unsigned*)((const char*)(gbase) + (voff)[_i]), (LAS unsigned*)(lds + (bufoff) + ldsw + _i * 8192), 16, 0, 0); } while (0)
; #define PG8_LDA(dst, b, h) do { _Pragma("unroll") for (int m = 0; m < 4; ++m) _Pragma("unroll") for (int k = 0; k < 2; ++k) dst[m][k] = *(const LAS bf16x8*)(lds + PG8_SA(b, h) + aoff + m * 2048 + k * 1024); } while (0)
; #define PG8_MMA(ai, bj, At, Bt) do { __builtin_amdgcn_s_setprio(1); _Pragma("unroll") for (int m = 0; m < 4; ++m) _Pragma("unroll") for (int n = 0; n < 2; ++n) _Pragma("unroll") for (int k = 0; k < 2; ++k) \
;         acc[ai][bj][m][n] = __builtin_amdgcn_mfma_f32_16x16x32_bf16(Bt[n][k], At[m][k], acc[ai][bj][m][n], 0, 0, 0); __builtin_amdgcn_s_setprio(0); } while (0)
; #define PG8_WAIT_V(n) asm volatile("s_waitcnt vmcnt(" #n ")" ::: "memory")
; #define PG8_WAIT_L(n) asm volatile("s_waitcnt lgkmcnt(" #n ")" ::: "memory")
; #define PG8_BAR __builtin_amdgcn_s_barrier()
; #define PG8_SCHED __builtin_amdgcn_sched_barrier(0)
; template <class Epi>
; __device__ __forceinline__ void gemm_phase(LAS unsigned char* lds, const Gemm g, const StaticOrder& S, const Epi& E) {
;     ...
;             PG8_LDA(At, 1, 1); PG8_STAGE(PG8_SB(1, 0), b3, voffB); PG8_STAGE(PG8_SB(1, 1), b3 + hstep, voffB); PG8_STAGE(PG8_SA(1, 0), a3, voffA);
;             PG8_WAIT_V(8); PG8_WAIT_L(0); PG8_BAR; PG8_MMA(1, 0, At, B0); PG8_MMA(1, 1, At, B1); PG8_BAR; PG8_SCHED;
;         }
	s_mov_b32 m0, s38
	v_lshl_add_u64 v[154:155], v[154:155], 0, s[82:83]
	ds_read_b128 v[182:185], v139 offset:49152
	ds_read_b128 v[186:189], v139 offset:50176
	ds_read_b128 v[190:193], v139 offset:51200
	ds_read_b128 v[194:197], v139 offset:52224
	ds_read_b128 v[198:201], v139 offset:53248
	ds_read_b128 v[202:205], v139 offset:54272
	ds_read_b128 v[206:209], v139 offset:55296
	ds_read_b128 v[226:229], v139 offset:56320
	global_load_lds_dwordx4 v[154:155], off
	v_lshl_add_u64 v[154:155], v[210:211], 0, s[82:83]
	s_mov_b32 m0, s39
	s_nop 0
	global_load_lds_dwordx4 v[154:155], off
	v_lshl_add_u64 v[154:155], v[216:217], 0, s[82:83]
	s_mov_b32 m0, s42
	s_nop 0
	global_load_lds_dwordx4 v[154:155], off
	v_lshl_add_u64 v[154:155], v[218:219], 0, s[82:83]
	s_mov_b32 m0, s43
	s_nop 0
	global_load_lds_dwordx4 v[154:155], off
	v_lshl_add_u64 v[154:155], v[220:221], 0, s[82:83]
	s_mov_b32 m0, s40
	s_nop 0
	global_load_lds_dwordx4 v[154:155], off
	v_lshl_add_u64 v[154:155], v[230:231], 0, s[82:83]
	s_mov_b32 m0, s41
	s_nop 0
	global_load_lds_dwordx4 v[154:155], off
	s_waitcnt vmcnt(8)
	s_waitcnt lgkmcnt(0)
	s_barrier
	s_waitcnt lgkmcnt(0)
	v_mfma_f32_16x16x32_bf16 v[60:63], v[142:145], v[182:185], v[60:63]
	v_mfma_f32_16x16x32_bf16 v[56:59], v[150:153], v[182:185], v[56:59]
	v_mfma_f32_16x16x32_bf16 v[44:47], v[142:145], v[190:193], v[44:47]
	v_mfma_f32_16x16x32_bf16 v[40:43], v[150:153], v[190:193], v[40:43]
	v_mfma_f32_16x16x32_bf16 v[28:31], v[142:145], v[198:201], v[28:31]
	v_mfma_f32_16x16x32_bf16 v[24:27], v[150:153], v[198:201], v[24:27]
	v_mfma_f32_16x16x32_bf16 v[12:15], v[142:145], v[206:209], v[12:15]
	v_mfma_f32_16x16x32_bf16 v[8:11], v[150:153], v[206:209], v[8:11]
	v_mfma_f32_16x16x32_bf16 v[60:63], v[146:149], v[186:189], v[60:63]
	v_mfma_f32_16x16x32_bf16 v[56:59], v[162:165], v[186:189], v[56:59]
	v_mfma_f32_16x16x32_bf16 v[44:47], v[146:149], v[194:197], v[44:47]
	v_mfma_f32_16x16x32_bf16 v[40:43], v[162:165], v[194:197], v[40:43]
	v_mfma_f32_16x16x32_bf16 v[28:31], v[146:149], v[202:205], v[28:31]
	v_mfma_f32_16x16x32_bf16 v[24:27], v[162:165], v[202:205], v[24:27]
	v_mfma_f32_16x16x32_bf16 v[12:15], v[146:149], v[226:229], v[12:15]
	v_mfma_f32_16x16x32_bf16 v[8:11], v[162:165], v[226:229], v[8:11]
	v_mfma_f32_16x16x32_bf16 v[52:55], v[166:169], v[182:185], v[52:55]
	v_mfma_f32_16x16x32_bf16 v[48:51], v[174:177], v[182:185], v[48:51]
	v_mfma_f32_16x16x32_bf16 v[36:39], v[166:169], v[190:193], v[36:39]
	v_mfma_f32_16x16x32_bf16 v[32:35], v[174:177], v[190:193], v[32:35]
	v_mfma_f32_16x16x32_bf16 v[20:23], v[166:169], v[198:201], v[20:23]
	v_mfma_f32_16x16x32_bf16 v[16:19], v[174:177], v[198:201], v[16:19]
	v_mfma_f32_16x16x32_bf16 v[4:7], v[166:169], v[206:209], v[4:7]
	v_mfma_f32_16x16x32_bf16 v[0:3], v[174:177], v[206:209], v[0:3]
	v_mfma_f32_16x16x32_bf16 v[52:55], v[170:173], v[186:189], v[52:55]
	v_mfma_f32_16x16x32_bf16 v[48:51], v[178:181], v[186:189], v[48:51]
	v_mfma_f32_16x16x32_bf16 v[36:39], v[170:173], v[194:197], v[36:39]
	v_mfma_f32_16x16x32_bf16 v[32:35], v[178:181], v[194:197], v[32:35]
	v_mfma_f32_16x16x32_bf16 v[20:23], v[170:173], v[202:205], v[20:23]
	v_mfma_f32_16x16x32_bf16 v[16:19], v[178:181], v[202:205], v[16:19]
	v_mfma_f32_16x16x32_bf16 v[4:7], v[170:173], v[226:229], v[4:7]
	v_mfma_f32_16x16x32_bf16 v[0:3], v[178:181], v[226:229], v[0:3]
	s_barrier
	s_add_u32 s18, s18, 0x100
	s_addc_u32 s19, s19, 0
	s_add_u32 s51, s51, 0x100
	s_addc_u32 s52, s52, 0
	s_cmp_ge_i32 s53, s44
	s_mov_b32 s20, s53
	s_cbranch_scc0 .LBB0_799

; #define PG8_STAGE(bufoff, gbase, voff) do { _Pragma("unroll") for (int _i = 0; _i < 2; ++_i) \
;         __builtin_amdgcn_global_load_lds((const unsigned*)((const char*)(gbase) + (voff)[_i]), (LAS unsigned*)(lds + (bufoff) + ldsw + _i * 8192), 16, 0, 0); } while (0)
; #define PG8_LDA(dst, b, h) do { _Pragma("unroll") for (int m = 0; m < 4; ++m) _Pragma("unroll") for (int k = 0; k < 2; ++k) dst[m][k] = *(const LAS bf16x8*)(lds + PG8_SA(b, h) + aoff + m * 2048 + k * 1024); } while (0)
; #define PG8_LDB(dst, b, h) do { _Pragma("unroll") for (int n = 0; n < 2; ++n) _Pragma("unroll") for (int k = 0; k < 2; ++k) dst[n][k] = *(const LAS bf16x8*)(lds + PG8_SB(b, h) + boff + n * 2048 + k * 1024); } while (0)
; #define PG8_MMA(ai, bj, At, Bt) do { __builtin_amdgcn_s_setprio(1); _Pragma("unroll") for (int m = 0; m < 4; ++m) _Pragma("unroll") for (int n = 0; n < 2; ++n) _Pragma("unroll") for (int k = 0; k < 2; ++k) \
;         acc[ai][bj][m][n] = __builtin_amdgcn_mfma_f32_16x16x32_bf16(Bt[n][k], At[m][k], acc[ai][bj][m][n], 0, 0, 0); __builtin_amdgcn_s_setprio(0); } while (0)
; #define PG8_WAIT_V(n) asm volatile("s_waitcnt vmcnt(" #n ")" ::: "memory")
; #define PG8_WAIT_L(n) asm volatile("s_waitcnt lgkmcnt(" #n ")" ::: "memory")
; #define PG8_BAR __builtin_amdgcn_s_barrier()
; #define PG8_SCHED __builtin_amdgcn_sched_barrier(0)
; template <class Epi>
; __device__ __forceinline__ void gemm_phase(LAS unsigned char* lds, const Gemm g, const StaticOrder& S, const Epi& E) {
;     ...
;             const bool last = (t == nt - 2);
;             const char* a1 = cA + (size_t)(t + 1) * kstep;
;             const char* a2 = last ? nA : cA + (size_t)(t + 2) * kstep; const char* b2 = last ? nB : cB + (size_t)(t + 2) * kstep;
;             const char* a3 = a2 + kstep; const char* b3 = b2 + kstep;
;             if (last && has_next) E.prep(nxt, (ui + 1) & 1, rsl, tid);
;             PG8_LDB(B0, 0, 0); PG8_LDB(B1, 0, 1); PG8_SCHED; PG8_LDA(At, 0, 0); PG8_STAGE(PG8_SA(1, 1), a1 + hstep, voffA);
;             PG8_WAIT_V(8); PG8_WAIT_L(0); PG8_BAR; PG8_MMA(0, 0, At, B0); PG8_MMA(0, 1, At, B1); PG8_BAR; PG8_SCHED;
;             PG8_LDA(At, 0, 1); PG8_STAGE(PG8_SB(0, 0), b2, voffB); PG8_STAGE(PG8_SB(0, 1), b2 + hstep, voffB); PG8_STAGE(PG8_SA(0, 0), a2, voffA);
;             PG8_WAIT_V(8); PG8_WAIT_L(0); PG8_BAR; PG8_MMA(1, 0, At, B0); PG8_MMA(1, 1, At, B1); PG8_BAR; PG8_SCHED;
.LBB0_830:
	v_or_b32_e32 v140, 0x10000, v150
	v_add_u32_e32 v144, 0x10400, v150
	v_add_u32_e32 v152, 0x10800, v150
	v_add_u32_e32 v156, 0x10c00, v150
	ds_read_b128 v[140:143], v140
	ds_read_b128 v[144:147], v144
	ds_read_b128 v[152:155], v152
	ds_read_b128 v[162:165], v156
	v_or_b32_e32 v156, 0x14000, v150
	v_add_u32_e32 v170, 0x14400, v150
	ds_read_b128 v[166:169], v156
	ds_read_b128 v[170:173], v170
	v_add_u32_e32 v156, 0x14800, v150
	v_add_u32_e32 v178, 0x14c00, v150
	s_add_i32 s68, s2, 2
	ds_read_b128 v[174:177], v156
	ds_read_b128 v[178:181], v178
	s_add_u32 s69, s0, 0x80
	s_addc_u32 s3, s1, 0
	s_cmp_eq_u32 s62, s2
	s_cselect_b32 s2, s8, s69
	s_cselect_b32 s3, s9, s3
	s_cselect_b32 s71, s35, s57
	s_cselect_b32 s70, s34, s56
	v_lshl_add_u64 v[210:211], s[0:1], 0, v[136:137]
	s_add_i32 m0, s44, 0xc000
	ds_read_b128 v[182:185], v149
	ds_read_b128 v[186:189], v149 offset:1024
	ds_read_b128 v[190:193], v149 offset:2048
	ds_read_b128 v[194:197], v149 offset:3072
	ds_read_b128 v[198:201], v149 offset:4096
	ds_read_b128 v[202:205], v149 offset:5120
	ds_read_b128 v[206:209], v149 offset:6144
	ds_read_b128 v[226:229], v149 offset:7168
	global_load_lds_dwordx4 v[210:211], off
	v_lshl_add_u64 v[210:211], s[0:1], 0, v[138:139]
	s_add_i32 m0, s44, 0xe000
	s_nop 0
	global_load_lds_dwordx4 v[210:211], off
	s_waitcnt vmcnt(8)
	s_waitcnt lgkmcnt(0)
	s_barrier
	s_waitcnt lgkmcnt(0)
	v_mfma_f32_16x16x32_bf16 v[120:123], v[140:143], v[182:185], v[120:123]
	v_mfma_f32_16x16x32_bf16 v[124:127], v[152:155], v[182:185], v[124:127]
	v_mfma_f32_16x16x32_bf16 v[108:111], v[140:143], v[190:193], v[108:111]
	v_mfma_f32_16x16x32_bf16 v[104:107], v[152:155], v[190:193], v[104:107]
	v_mfma_f32_16x16x32_bf16 v[92:95], v[140:143], v[198:201], v[92:95]
	v_mfma_f32_16x16x32_bf16 v[88:91], v[152:155], v[198:201], v[88:91]
	v_mfma_f32_16x16x32_bf16 v[76:79], v[140:143], v[206:209], v[76:79]
	v_mfma_f32_16x16x32_bf16 v[72:75], v[152:155], v[206:209], v[72:75]
	v_mfma_f32_16x16x32_bf16 v[120:123], v[144:147], v[186:189], v[120:123]
	v_mfma_f32_16x16x32_bf16 v[124:127], v[162:165], v[186:189], v[124:127]
	v_mfma_f32_16x16x32_bf16 v[108:111], v[144:147], v[194:197], v[108:111]
	v_mfma_f32_16x16x32_bf16 v[104:107], v[162:165], v[194:197], v[104:107]
	v_mfma_f32_16x16x32_bf16 v[92:95], v[144:147], v[202:205], v[92:95]
	v_mfma_f32_16x16x32_bf16 v[88:91], v[162:165], v[202:205], v[88:91]
	v_mfma_f32_16x16x32_bf16 v[76:79], v[144:147], v[226:229], v[76:79]
	v_mfma_f32_16x16x32_bf16 v[72:75], v[162:165], v[226:229], v[72:75]
	v_mfma_f32_16x16x32_bf16 v[116:119], v[166:169], v[182:185], v[116:119]
	v_mfma_f32_16x16x32_bf16 v[112:115], v[174:177], v[182:185], v[112:115]
	v_mfma_f32_16x16x32_bf16 v[100:103], v[166:169], v[190:193], v[100:103]
	v_mfma_f32_16x16x32_bf16 v[96:99], v[174:177], v[190:193], v[96:99]
	v_mfma_f32_16x16x32_bf16 v[84:87], v[166:169], v[198:201], v[84:87]
	v_mfma_f32_16x16x32_bf16 v[80:83], v[174:177], v[198:201], v[80:83]
	v_mfma_f32_16x16x32_bf16 v[68:71], v[166:169], v[206:209], v[68:71]
	v_mfma_f32_16x16x32_bf16 v[64:67], v[174:177], v[206:209], v[64:67]
	v_mfma_f32_16x16x32_bf16 v[116:119], v[170:173], v[186:189], v[116:119]
	v_mfma_f32_16x16x32_bf16 v[112:115], v[178:181], v[186:189], v[112:115]
	v_mfma_f32_16x16x32_bf16 v[100:103], v[170:173], v[194:197], v[100:103]
	v_mfma_f32_16x16x32_bf16 v[96:99], v[178:181], v[194:197], v[96:99]
	v_mfma_f32_16x16x32_bf16 v[84:87], v[170:173], v[202:205], v[84:87]
	v_mfma_f32_16x16x32_bf16 v[80:83], v[178:181], v[202:205], v[80:83]
	v_mfma_f32_16x16x32_bf16 v[68:71], v[170:173], v[226:229], v[68:71]
	v_mfma_f32_16x16x32_bf16 v[64:67], v[178:181], v[226:229], v[64:67]
	s_barrier
	s_mov_b32 m0, s45
	v_lshl_add_u64 v[210:211], s[70:71], 0, v[130:131]
	v_lshl_add_u64 v[216:217], s[70:71], 0, v[134:135]
	s_add_u32 s70, s70, s16
	ds_read_b128 v[182:185], v149 offset:16384
	ds_read_b128 v[186:189], v149 offset:17408
	ds_read_b128 v[190:193], v149 offset:18432
	ds_read_b128 v[194:197], v149 offset:19456
	ds_read_b128 v[198:201], v149 offset:20480
	ds_read_b128 v[202:205], v149 offset:21504
	ds_read_b128 v[206:209], v149 offset:22528
	ds_read_b128 v[226:229], v149 offset:23552
	global_load_lds_dwordx4 v[210:211], off
	s_mov_b32 m0, s46
	s_addc_u32 s71, s71, s17
	global_load_lds_dwordx4 v[216:217], off
	v_lshl_add_u64 v[218:219], s[70:71], 0, v[130:131]
	s_mov_b32 m0, s47
	v_lshl_add_u64 v[220:221], s[70:71], 0, v[134:135]
	global_load_lds_dwordx4 v[218:219], off
	s_mov_b32 m0, s48
	v_lshl_add_u64 v[230:231], s[2:3], 0, v[128:129]
	global_load_lds_dwordx4 v[220:221], off
	s_mov_b32 m0, s44
	v_lshl_add_u64 v[232:233], s[2:3], 0, v[132:133]
	global_load_lds_dwordx4 v[230:231], off
	s_mov_b32 m0, s49
	s_nop 0
	global_load_lds_dwordx4 v[232:233], off
	s_waitcnt vmcnt(8)
	s_waitcnt lgkmcnt(0)
	s_barrier
; #define PG8_STAGE(bufoff, gbase, voff) do { _Pragma("unroll") for (int _i = 0; _i < 2; ++_i) \
;         __builtin_amdgcn_global_load_lds((const unsigned*)((const char*)(gbase) + (voff)[_i]), (LAS unsigned*)(lds + (bufoff) + ldsw + _i * 8192), 16, 0, 0); } while (0)
; #define PG8_LDA(dst, b, h) do { _Pragma("unroll") for (int m = 0; m < 4; ++m) _Pragma("unroll") for (int k = 0; k < 2; ++k) dst[m][k] = *(const LAS bf16x8*)(lds + PG8_SA(b, h) + aoff + m * 2048 + k * 1024); } while (0)
; #define PG8_LDB(dst, b, h) do { _Pragma("unroll") for (int n = 0; n < 2; ++n) _Pragma("unroll") for (int k = 0; k < 2; ++k) dst[n][k] = *(const LAS bf16x8*)(lds + PG8_SB(b, h) + boff + n * 2048 + k * 1024); } while (0)
; #define PG8_MMA(ai, bj, At, Bt) do { __builtin_amdgcn_s_setprio(1); _Pragma("unroll") for (int m = 0; m < 4; ++m) _Pragma("unroll") for (int n = 0; n < 2; ++n) _Pragma("unroll") for (int k = 0; k < 2; ++k) \
;         acc[ai][bj][m][n] = __builtin_amdgcn_mfma_f32_16x16x32_bf16(Bt[n][k], At[m][k], acc[ai][bj][m][n], 0, 0, 0); __builtin_amdgcn_s_setprio(0); } while (0)
; #define PG8_WAIT_V(n) asm volatile("s_waitcnt vmcnt(" #n ")" ::: "memory")
; #define PG8_WAIT_L(n) asm volatile("s_waitcnt lgkmcnt(" #n ")" ::: "memory")
; #define PG8_BAR __builtin_amdgcn_s_barrier()
; #define PG8_SCHED __builtin_amdgcn_sched_barrier(0)
; template <class Epi>
; __device__ __forceinline__ void gemm_phase(LAS unsigned char* lds, const Gemm g, const StaticOrder& S, const Epi& E) {
;     ...
;             PG8_WAIT_V(8); PG8_WAIT_L(0); PG8_BAR; PG8_MMA(1, 0, At, B0); PG8_MMA(1, 1, At, B1); PG8_BAR; PG8_SCHED;
;             PG8_LDB(B0, 1, 0); PG8_LDB(B1, 1, 1); PG8_SCHED; PG8_LDA(At, 1, 0); PG8_STAGE(PG8_SA(0, 1), a2 + hstep, voffA);
;             PG8_WAIT_V(8); PG8_WAIT_L(0); PG8_BAR; PG8_MMA(0, 0, At, B0); PG8_MMA(0, 1, At, B1); PG8_BAR; PG8_SCHED;
	s_waitcnt lgkmcnt(0)
	v_mfma_f32_16x16x32_bf16 v[60:63], v[140:143], v[182:185], v[60:63]
	v_mfma_f32_16x16x32_bf16 v[56:59], v[152:155], v[182:185], v[56:59]
	v_mfma_f32_16x16x32_bf16 v[44:47], v[140:143], v[190:193], v[44:47]
	v_mfma_f32_16x16x32_bf16 v[40:43], v[152:155], v[190:193], v[40:43]
	v_mfma_f32_16x16x32_bf16 v[28:31], v[140:143], v[198:201], v[28:31]
	v_mfma_f32_16x16x32_bf16 v[24:27], v[152:155], v[198:201], v[24:27]
	v_mfma_f32_16x16x32_bf16 v[12:15], v[140:143], v[206:209], v[12:15]
	v_mfma_f32_16x16x32_bf16 v[8:11], v[152:155], v[206:209], v[8:11]
	v_mfma_f32_16x16x32_bf16 v[60:63], v[144:147], v[186:189], v[60:63]
	v_mfma_f32_16x16x32_bf16 v[56:59], v[162:165], v[186:189], v[56:59]
	v_mfma_f32_16x16x32_bf16 v[44:47], v[144:147], v[194:197], v[44:47]
	v_mfma_f32_16x16x32_bf16 v[40:43], v[162:165], v[194:197], v[40:43]
	v_mfma_f32_16x16x32_bf16 v[28:31], v[144:147], v[202:205], v[28:31]
	v_mfma_f32_16x16x32_bf16 v[24:27], v[162:165], v[202:205], v[24:27]
	v_mfma_f32_16x16x32_bf16 v[12:15], v[144:147], v[226:229], v[12:15]
	v_mfma_f32_16x16x32_bf16 v[8:11], v[162:165], v[226:229], v[8:11]
	v_mfma_f32_16x16x32_bf16 v[52:55], v[166:169], v[182:185], v[52:55]
	v_mfma_f32_16x16x32_bf16 v[48:51], v[174:177], v[182:185], v[48:51]
	v_mfma_f32_16x16x32_bf16 v[36:39], v[166:169], v[190:193], v[36:39]
	v_mfma_f32_16x16x32_bf16 v[32:35], v[174:177], v[190:193], v[32:35]
	v_mfma_f32_16x16x32_bf16 v[20:23], v[166:169], v[198:201], v[20:23]
	v_mfma_f32_16x16x32_bf16 v[16:19], v[174:177], v[198:201], v[16:19]
	v_mfma_f32_16x16x32_bf16 v[4:7], v[166:169], v[206:209], v[4:7]
	v_mfma_f32_16x16x32_bf16 v[0:3], v[174:177], v[206:209], v[0:3]
	v_mfma_f32_16x16x32_bf16 v[52:55], v[170:173], v[186:189], v[52:55]
	v_mfma_f32_16x16x32_bf16 v[48:51], v[178:181], v[186:189], v[48:51]
	v_mfma_f32_16x16x32_bf16 v[36:39], v[170:173], v[194:197], v[36:39]
	v_mfma_f32_16x16x32_bf16 v[32:35], v[178:181], v[194:197], v[32:35]
	v_mfma_f32_16x16x32_bf16 v[20:23], v[170:173], v[202:205], v[20:23]
	v_mfma_f32_16x16x32_bf16 v[16:19], v[178:181], v[202:205], v[16:19]
	v_mfma_f32_16x16x32_bf16 v[4:7], v[170:173], v[226:229], v[4:7]
	v_mfma_f32_16x16x32_bf16 v[0:3], v[178:181], v[226:229], v[0:3]
	s_barrier
	v_or_b32_e32 v140, 0x18000, v150
	v_add_u32_e32 v144, 0x18400, v150
	v_add_u32_e32 v152, 0x18800, v150
	v_add_u32_e32 v156, 0x18c00, v150
	ds_read_b128 v[140:143], v140
	ds_read_b128 v[144:147], v144
	ds_read_b128 v[152:155], v152
	ds_read_b128 v[162:165], v156
	v_or_b32_e32 v156, 0x1c000, v150
	v_add_u32_e32 v170, 0x1c400, v150
	ds_read_b128 v[166:169], v156
	ds_read_b128 v[170:173], v170
	v_add_u32_e32 v156, 0x1c800, v150
	v_add_u32_e32 v178, 0x1cc00, v150
	ds_read_b128 v[174:177], v156
	ds_read_b128 v[178:181], v178
	s_add_u32 s2, s2, s16
	s_addc_u32 s3, s3, s17
	s_mov_b32 m0, s50
	v_lshl_add_u64 v[234:235], s[2:3], 0, v[128:129]
	ds_read_b128 v[182:185], v149 offset:32768
	ds_read_b128 v[186:189], v149 offset:33792
	ds_read_b128 v[190:193], v149 offset:34816
	ds_read_b128 v[194:197], v149 offset:35840
	ds_read_b128 v[198:201], v149 offset:36864
	ds_read_b128 v[202:205], v149 offset:37888
	ds_read_b128 v[206:209], v149 offset:38912
	ds_read_b128 v[226:229], v149 offset:39936
	global_load_lds_dwordx4 v[234:235], off
	v_lshl_add_u64 v[234:235], s[2:3], 0, v[132:133]
	s_mov_b32 m0, s51
	s_nop 0
	global_load_lds_dwordx4 v[234:235], off
	s_waitcnt vmcnt(8)
	s_waitcnt lgkmcnt(0)
	s_barrier
	s_waitcnt lgkmcnt(0)
	v_mfma_f32_16x16x32_bf16 v[120:123], v[140:143], v[182:185], v[120:123]
	v_mfma_f32_16x16x32_bf16 v[124:127], v[152:155], v[182:185], v[124:127]
	v_mfma_f32_16x16x32_bf16 v[108:111], v[140:143], v[190:193], v[108:111]
	v_mfma_f32_16x16x32_bf16 v[104:107], v[152:155], v[190:193], v[104:107]
	v_mfma_f32_16x16x32_bf16 v[92:95], v[140:143], v[198:201], v[92:95]
	v_mfma_f32_16x16x32_bf16 v[88:91], v[152:155], v[198:201], v[88:91]
	v_mfma_f32_16x16x32_bf16 v[76:79], v[140:143], v[206:209], v[76:79]
	v_mfma_f32_16x16x32_bf16 v[72:75], v[152:155], v[206:209], v[72:75]
	v_mfma_f32_16x16x32_bf16 v[120:123], v[144:147], v[186:189], v[120:123]
	v_mfma_f32_16x16x32_bf16 v[124:127], v[162:165], v[186:189], v[124:127]
	v_mfma_f32_16x16x32_bf16 v[108:111], v[144:147], v[194:197], v[108:111]
	v_mfma_f32_16x16x32_bf16 v[104:107], v[162:165], v[194:197], v[104:107]
	v_mfma_f32_16x16x32_bf16 v[92:95], v[144:147], v[202:205], v[92:95]
	v_mfma_f32_16x16x32_bf16 v[88:91], v[162:165], v[202:205], v[88:91]
	v_mfma_f32_16x16x32_bf16 v[76:79], v[144:147], v[226:229], v[76:79]
	v_mfma_f32_16x16x32_bf16 v[72:75], v[162:165], v[226:229], v[72:75]
	v_mfma_f32_16x16x32_bf16 v[116:119], v[166:169], v[182:185], v[116:119]
	v_mfma_f32_16x16x32_bf16 v[112:115], v[174:177], v[182:185], v[112:115]
	v_mfma_f32_16x16x32_bf16 v[100:103], v[166:169], v[190:193], v[100:103]
	v_mfma_f32_16x16x32_bf16 v[96:99], v[174:177], v[190:193], v[96:99]
	v_mfma_f32_16x16x32_bf16 v[84:87], v[166:169], v[198:201], v[84:87]
	v_mfma_f32_16x16x32_bf16 v[80:83], v[174:177], v[198:201], v[80:83]
	v_mfma_f32_16x16x32_bf16 v[68:71], v[166:169], v[206:209], v[68:71]
	v_mfma_f32_16x16x32_bf16 v[64:67], v[174:177], v[206:209], v[64:67]
	v_mfma_f32_16x16x32_bf16 v[116:119], v[170:173], v[186:189], v[116:119]
	v_mfma_f32_16x16x32_bf16 v[112:115], v[178:181], v[186:189], v[112:115]
	v_mfma_f32_16x16x32_bf16 v[100:103], v[170:173], v[194:197], v[100:103]
	v_mfma_f32_16x16x32_bf16 v[96:99], v[178:181], v[194:197], v[96:99]
	v_mfma_f32_16x16x32_bf16 v[84:87], v[170:173], v[202:205], v[84:87]
	v_mfma_f32_16x16x32_bf16 v[80:83], v[178:181], v[202:205], v[80:83]
	v_mfma_f32_16x16x32_bf16 v[68:71], v[170:173], v[226:229], v[68:71]
	v_mfma_f32_16x16x32_bf16 v[64:67], v[178:181], v[226:229], v[64:67]
	s_barrier
; #define PG8_STAGE(bufoff, gbase, voff) do { _Pragma("unroll") for (int _i = 0; _i < 2; ++_i) \
;         __builtin_amdgcn_global_load_lds((const unsigned*)((const char*)(gbase) + (voff)[_i]), (LAS unsigned*)(lds + (bufoff) + ldsw + _i * 8192), 16, 0, 0); } while (0)
; #define PG8_LDA(dst, b, h) do { _Pragma("unroll") for (int m = 0; m < 4; ++m) _Pragma("unroll") for (int k = 0; k < 2; ++k) dst[m][k] = *(const LAS bf16x8*)(lds + PG8_SA(b, h) + aoff + m * 2048 + k * 1024); } while (0)
; #define PG8_MMA(ai, bj, At, Bt) do { __builtin_amdgcn_s_setprio(1); _Pragma("unroll") for (int m = 0; m < 4; ++m) _Pragma("unroll") for (int n = 0; n < 2; ++n) _Pragma("unroll") for (int k = 0; k < 2; ++k) \
;         acc[ai][bj][m][n] = __builtin_amdgcn_mfma_f32_16x16x32_bf16(Bt[n][k], At[m][k], acc[ai][bj][m][n], 0, 0, 0); __builtin_amdgcn_s_setprio(0); } while (0)
; #define PG8_WAIT_V(n) asm volatile("s_waitcnt vmcnt(" #n ")" ::: "memory")
; #define PG8_WAIT_L(n) asm volatile("s_waitcnt lgkmcnt(" #n ")" ::: "memory")
; #define PG8_BAR __builtin_amdgcn_s_barrier()
; #define PG8_SCHED __builtin_amdgcn_sched_barrier(0)
; template <class Epi>
; __device__ __forceinline__ void gemm_phase(LAS unsigned char* lds, const Gemm g, const StaticOrder& S, const Epi& E) {
;     ...
;             PG8_LDA(At, 1, 1); PG8_STAGE(PG8_SB(1, 0), b3, voffB); PG8_STAGE(PG8_SB(1, 1), b3 + hstep, voffB); PG8_STAGE(PG8_SA(1, 0), a3, voffA);
;             PG8_WAIT_V(8); PG8_WAIT_L(0); PG8_BAR; PG8_MMA(1, 0, At, B0); PG8_MMA(1, 1, At, B1); PG8_BAR; PG8_SCHED;
;         }
	s_mov_b32 m0, s52
	v_lshl_add_u64 v[210:211], v[210:211], 0, s[82:83]
	ds_read_b128 v[182:185], v149 offset:49152
	ds_read_b128 v[186:189], v149 offset:50176
	ds_read_b128 v[190:193], v149 offset:51200
	ds_read_b128 v[194:197], v149 offset:52224
	ds_read_b128 v[198:201], v149 offset:53248
	ds_read_b128 v[202:205], v149 offset:54272
	ds_read_b128 v[206:209], v149 offset:55296
	ds_read_b128 v[226:229], v149 offset:56320
	global_load_lds_dwordx4 v[210:211], off
	v_lshl_add_u64 v[210:211], v[216:217], 0, s[82:83]
	s_mov_b32 m0, s53
	s_nop 0
	global_load_lds_dwordx4 v[210:211], off
	v_lshl_add_u64 v[210:211], v[218:219], 0, s[82:83]
	s_mov_b32 m0, s58
	s_nop 0
	global_load_lds_dwordx4 v[210:211], off
	v_lshl_add_u64 v[210:211], v[220:221], 0, s[82:83]
	s_mov_b32 m0, s59
	s_nop 0
	global_load_lds_dwordx4 v[210:211], off
	v_lshl_add_u64 v[210:211], v[230:231], 0, s[82:83]
	s_mov_b32 m0, s54
	s_nop 0
	global_load_lds_dwordx4 v[210:211], off
	v_lshl_add_u64 v[210:211], v[232:233], 0, s[82:83]
	s_mov_b32 m0, s55
	s_nop 0
	global_load_lds_dwordx4 v[210:211], off
	s_waitcnt vmcnt(8)
	s_waitcnt lgkmcnt(0)
	s_barrier
	s_waitcnt lgkmcnt(0)
	v_mfma_f32_16x16x32_bf16 v[60:63], v[140:143], v[182:185], v[60:63]
	v_mfma_f32_16x16x32_bf16 v[56:59], v[152:155], v[182:185], v[56:59]
	v_mfma_f32_16x16x32_bf16 v[44:47], v[140:143], v[190:193], v[44:47]
	v_mfma_f32_16x16x32_bf16 v[40:43], v[152:155], v[190:193], v[40:43]
	v_mfma_f32_16x16x32_bf16 v[28:31], v[140:143], v[198:201], v[28:31]
	v_mfma_f32_16x16x32_bf16 v[24:27], v[152:155], v[198:201], v[24:27]
	v_mfma_f32_16x16x32_bf16 v[12:15], v[140:143], v[206:209], v[12:15]
	v_mfma_f32_16x16x32_bf16 v[8:11], v[152:155], v[206:209], v[8:11]
	v_mfma_f32_16x16x32_bf16 v[60:63], v[144:147], v[186:189], v[60:63]
	v_mfma_f32_16x16x32_bf16 v[56:59], v[162:165], v[186:189], v[56:59]
	v_mfma_f32_16x16x32_bf16 v[44:47], v[144:147], v[194:197], v[44:47]
	v_mfma_f32_16x16x32_bf16 v[40:43], v[162:165], v[194:197], v[40:43]
	v_mfma_f32_16x16x32_bf16 v[28:31], v[144:147], v[202:205], v[28:31]
	v_mfma_f32_16x16x32_bf16 v[24:27], v[162:165], v[202:205], v[24:27]
	v_mfma_f32_16x16x32_bf16 v[12:15], v[144:147], v[226:229], v[12:15]
	v_mfma_f32_16x16x32_bf16 v[8:11], v[162:165], v[226:229], v[8:11]
	v_mfma_f32_16x16x32_bf16 v[52:55], v[166:169], v[182:185], v[52:55]
	v_mfma_f32_16x16x32_bf16 v[48:51], v[174:177], v[182:185], v[48:51]
	v_mfma_f32_16x16x32_bf16 v[36:39], v[166:169], v[190:193], v[36:39]
	v_mfma_f32_16x16x32_bf16 v[32:35], v[174:177], v[190:193], v[32:35]
	v_mfma_f32_16x16x32_bf16 v[20:23], v[166:169], v[198:201], v[20:23]
	v_mfma_f32_16x16x32_bf16 v[16:19], v[174:177], v[198:201], v[16:19]
	v_mfma_f32_16x16x32_bf16 v[4:7], v[166:169], v[206:209], v[4:7]
	v_mfma_f32_16x16x32_bf16 v[0:3], v[174:177], v[206:209], v[0:3]
	v_mfma_f32_16x16x32_bf16 v[52:55], v[170:173], v[186:189], v[52:55]
	v_mfma_f32_16x16x32_bf16 v[48:51], v[178:181], v[186:189], v[48:51]
	v_mfma_f32_16x16x32_bf16 v[36:39], v[170:173], v[194:197], v[36:39]
	v_mfma_f32_16x16x32_bf16 v[32:35], v[178:181], v[194:197], v[32:35]
	v_mfma_f32_16x16x32_bf16 v[20:23], v[170:173], v[202:205], v[20:23]
	v_mfma_f32_16x16x32_bf16 v[16:19], v[178:181], v[202:205], v[16:19]
	v_mfma_f32_16x16x32_bf16 v[4:7], v[170:173], v[226:229], v[4:7]
	v_mfma_f32_16x16x32_bf16 v[0:3], v[178:181], v[226:229], v[0:3]
	s_barrier
	s_add_u32 s0, s0, 0x100
	s_addc_u32 s1, s1, 0
	s_add_u32 s56, s56, 0x100
	s_addc_u32 s57, s57, 0
	s_cmp_ge_i32 s68, s61
	s_mov_b32 s2, s68
	s_cbranch_scc0 .LBB0_830

; #define PG8_STAGE(bufoff, gbase, voff) do { _Pragma("unroll") for (int _i = 0; _i < 2; ++_i) \
;         __builtin_amdgcn_global_load_lds((const unsigned*)((const char*)(gbase) + (voff)[_i]), (LAS unsigned*)(lds + (bufoff) + ldsw + _i * 8192), 16, 0, 0); } while (0)
; #define PG8_LDA(dst, b, h) do { _Pragma("unroll") for (int m = 0; m < 4; ++m) _Pragma("unroll") for (int k = 0; k < 2; ++k) dst[m][k] = *(const LAS bf16x8*)(lds + PG8_SA(b, h) + aoff + m * 2048 + k * 1024); } while (0)
; #define PG8_LDB(dst, b, h) do { _Pragma("unroll") for (int n = 0; n < 2; ++n) _Pragma("unroll") for (int k = 0; k < 2; ++k) dst[n][k] = *(const LAS bf16x8*)(lds + PG8_SB(b, h) + boff + n * 2048 + k * 1024); } while (0)
; #define PG8_MMA(ai, bj, At, Bt) do { __builtin_amdgcn_s_setprio(1); _Pragma("unroll") for (int m = 0; m < 4; ++m) _Pragma("unroll") for (int n = 0; n < 2; ++n) _Pragma("unroll") for (int k = 0; k < 2; ++k) \
;         acc[ai][bj][m][n] = __builtin_amdgcn_mfma_f32_16x16x32_bf16(Bt[n][k], At[m][k], acc[ai][bj][m][n], 0, 0, 0); __builtin_amdgcn_s_setprio(0); } while (0)
; #define PG8_WAIT_V(n) asm volatile("s_waitcnt vmcnt(" #n ")" ::: "memory")
; #define PG8_WAIT_L(n) asm volatile("s_waitcnt lgkmcnt(" #n ")" ::: "memory")
; #define PG8_BAR __builtin_amdgcn_s_barrier()
; #define PG8_SCHED __builtin_amdgcn_sched_barrier(0)
; template <class Epi>
; __device__ __forceinline__ void gemm_phase(LAS unsigned char* lds, const Gemm g, const StaticOrder& S, const Epi& E) {
;     ...
;             if (last && has_next) E.prep(nxt, (ui + 1) & 1, rsl, tid);
;             PG8_LDB(B0, 0, 0); PG8_LDB(B1, 0, 1); PG8_SCHED; PG8_LDA(At, 0, 0); PG8_STAGE(PG8_SA(1, 1), a1 + hstep, voffA);
;             PG8_WAIT_V(8); PG8_WAIT_L(0); PG8_BAR; PG8_MMA(0, 0, At, B0); PG8_MMA(0, 1, At, B1); PG8_BAR; PG8_SCHED;
;             PG8_LDA(At, 0, 1); PG8_STAGE(PG8_SB(0, 0), b2, voffB); PG8_STAGE(PG8_SB(0, 1), b2 + hstep, voffB); PG8_STAGE(PG8_SA(0, 0), a2, voffA);
;             PG8_WAIT_V(8); PG8_WAIT_L(0); PG8_BAR; PG8_MMA(1, 0, At, B0); PG8_MMA(1, 1, At, B1); PG8_BAR; PG8_SCHED;
.LBB0_983:
	s_or_b64 exec, exec, s[38:39]
	v_or_b32_e32 v141, 0x10000, v162
	v_add_u32_e32 v142, 0x10400, v162
	ds_read_b128 v[146:149], v141
	ds_read_b128 v[150:153], v142
	v_add_u32_e32 v141, 0x10800, v162
	v_add_u32_e32 v142, 0x10c00, v162
	ds_read_b128 v[170:173], v141
	ds_read_b128 v[174:177], v142
	v_or_b32_e32 v141, 0x14000, v162
	v_add_u32_e32 v142, 0x14400, v162
	ds_read_b128 v[178:181], v141
	ds_read_b128 v[182:185], v142
	v_add_u32_e32 v141, 0x14800, v162
	v_add_u32_e32 v142, 0x14c00, v162
	ds_read_b128 v[186:189], v141
	ds_read_b128 v[190:193], v142
	s_add_i32 s71, s71, 2
	s_add_u32 s38, s2, 0x80
	s_addc_u32 s39, s3, 0
	s_and_b64 s[10:11], s[10:11], exec
	s_cselect_b32 s11, s39, s13
	s_cselect_b32 s10, s38, s12
	s_cselect_b32 s39, s70, s37
	s_cselect_b32 s38, s69, s36
	v_lshl_add_u64 v[142:143], s[2:3], 0, v[134:135]
	s_add_i32 m0, s44, 0xc000
	ds_read_b128 v[194:197], v155
	ds_read_b128 v[198:201], v155 offset:1024
	ds_read_b128 v[202:205], v155 offset:2048
	ds_read_b128 v[206:209], v155 offset:3072
	ds_read_b128 v[226:229], v155 offset:4096
	ds_read_b128 v[230:233], v155 offset:5120
	ds_read_b128 v[234:237], v155 offset:6144
	ds_read_b128 v[238:241], v155 offset:7168
	global_load_lds_dwordx4 v[142:143], off
	v_lshl_add_u64 v[142:143], s[2:3], 0, v[136:137]
	s_add_i32 m0, s44, 0xe000
	s_nop 0
	global_load_lds_dwordx4 v[142:143], off
	s_waitcnt vmcnt(8)
	s_waitcnt lgkmcnt(0)
	s_barrier
	s_waitcnt lgkmcnt(0)
	v_mfma_f32_16x16x32_bf16 v[120:123], v[146:149], v[194:197], v[120:123]
	v_mfma_f32_16x16x32_bf16 v[124:127], v[170:173], v[194:197], v[124:127]
	v_mfma_f32_16x16x32_bf16 v[108:111], v[146:149], v[202:205], v[108:111]
	v_mfma_f32_16x16x32_bf16 v[104:107], v[170:173], v[202:205], v[104:107]
	v_mfma_f32_16x16x32_bf16 v[92:95], v[146:149], v[226:229], v[92:95]
	v_mfma_f32_16x16x32_bf16 v[88:91], v[170:173], v[226:229], v[88:91]
	v_mfma_f32_16x16x32_bf16 v[76:79], v[146:149], v[234:237], v[76:79]
	v_mfma_f32_16x16x32_bf16 v[72:75], v[170:173], v[234:237], v[72:75]
	v_mfma_f32_16x16x32_bf16 v[120:123], v[150:153], v[198:201], v[120:123]
	v_mfma_f32_16x16x32_bf16 v[124:127], v[174:177], v[198:201], v[124:127]
	v_mfma_f32_16x16x32_bf16 v[108:111], v[150:153], v[206:209], v[108:111]
	v_mfma_f32_16x16x32_bf16 v[104:107], v[174:177], v[206:209], v[104:107]
	v_mfma_f32_16x16x32_bf16 v[92:95], v[150:153], v[230:233], v[92:95]
	v_mfma_f32_16x16x32_bf16 v[88:91], v[174:177], v[230:233], v[88:91]
	v_mfma_f32_16x16x32_bf16 v[76:79], v[150:153], v[238:241], v[76:79]
	v_mfma_f32_16x16x32_bf16 v[72:75], v[174:177], v[238:241], v[72:75]
	v_mfma_f32_16x16x32_bf16 v[116:119], v[178:181], v[194:197], v[116:119]
	v_mfma_f32_16x16x32_bf16 v[112:115], v[186:189], v[194:197], v[112:115]
	v_mfma_f32_16x16x32_bf16 v[100:103], v[178:181], v[202:205], v[100:103]
	v_mfma_f32_16x16x32_bf16 v[96:99], v[186:189], v[202:205], v[96:99]
	v_mfma_f32_16x16x32_bf16 v[84:87], v[178:181], v[226:229], v[84:87]
	v_mfma_f32_16x16x32_bf16 v[80:83], v[186:189], v[226:229], v[80:83]
	v_mfma_f32_16x16x32_bf16 v[68:71], v[178:181], v[234:237], v[68:71]
	v_mfma_f32_16x16x32_bf16 v[64:67], v[186:189], v[234:237], v[64:67]
	v_mfma_f32_16x16x32_bf16 v[116:119], v[182:185], v[198:201], v[116:119]
	v_mfma_f32_16x16x32_bf16 v[112:115], v[190:193], v[198:201], v[112:115]
	v_mfma_f32_16x16x32_bf16 v[100:103], v[182:185], v[206:209], v[100:103]
	v_mfma_f32_16x16x32_bf16 v[96:99], v[190:193], v[206:209], v[96:99]
	v_mfma_f32_16x16x32_bf16 v[84:87], v[182:185], v[230:233], v[84:87]
	v_mfma_f32_16x16x32_bf16 v[80:83], v[190:193], v[230:233], v[80:83]
	v_mfma_f32_16x16x32_bf16 v[68:71], v[182:185], v[238:241], v[68:71]
	v_mfma_f32_16x16x32_bf16 v[64:67], v[190:193], v[238:241], v[64:67]
	s_barrier
	s_mov_b32 m0, s45
	v_lshl_add_u64 v[142:143], s[38:39], 0, v[156:157]
	v_lshl_add_u64 v[210:211], s[38:39], 0, v[132:133]
	s_add_u32 s38, s38, s20
	ds_read_b128 v[194:197], v155 offset:16384
	ds_read_b128 v[198:201], v155 offset:17408
	ds_read_b128 v[202:205], v155 offset:18432
	ds_read_b128 v[206:209], v155 offset:19456
	ds_read_b128 v[226:229], v155 offset:20480
	ds_read_b128 v[230:233], v155 offset:21504
	ds_read_b128 v[234:237], v155 offset:22528
	ds_read_b128 v[238:241], v155 offset:23552
	global_load_lds_dwordx4 v[142:143], off
	s_mov_b32 m0, s46
	s_addc_u32 s39, s39, s21
	global_load_lds_dwordx4 v[210:211], off
	v_lshl_add_u64 v[216:217], s[38:39], 0, v[156:157]
	s_mov_b32 m0, s47
	v_lshl_add_u64 v[218:219], s[38:39], 0, v[132:133]
	global_load_lds_dwordx4 v[216:217], off
	s_mov_b32 m0, s48
	v_lshl_add_u64 v[220:221], s[10:11], 0, v[128:129]
	global_load_lds_dwordx4 v[218:219], off
	s_mov_b32 m0, s44
	v_lshl_add_u64 v[242:243], s[10:11], 0, v[130:131]
	global_load_lds_dwordx4 v[220:221], off
	s_mov_b32 m0, s49
	s_nop 0
	global_load_lds_dwordx4 v[242:243], off
	s_waitcnt vmcnt(8)
	s_waitcnt lgkmcnt(0)
	s_barrier
; #define PG8_STAGE(bufoff, gbase, voff) do { _Pragma("unroll") for (int _i = 0; _i < 2; ++_i) \
;         __builtin_amdgcn_global_load_lds((const unsigned*)((const char*)(gbase) + (voff)[_i]), (LAS unsigned*)(lds + (bufoff) + ldsw + _i * 8192), 16, 0, 0); } while (0)
; #define PG8_LDA(dst, b, h) do { _Pragma("unroll") for (int m = 0; m < 4; ++m) _Pragma("unroll") for (int k = 0; k < 2; ++k) dst[m][k] = *(const LAS bf16x8*)(lds + PG8_SA(b, h) + aoff + m * 2048 + k * 1024); } while (0)
; #define PG8_LDB(dst, b, h) do { _Pragma("unroll") for (int n = 0; n < 2; ++n) _Pragma("unroll") for (int k = 0; k < 2; ++k) dst[n][k] = *(const LAS bf16x8*)(lds + PG8_SB(b, h) + boff + n * 2048 + k * 1024); } while (0)
; #define PG8_MMA(ai, bj, At, Bt) do { __builtin_amdgcn_s_setprio(1); _Pragma("unroll") for (int m = 0; m < 4; ++m) _Pragma("unroll") for (int n = 0; n < 2; ++n) _Pragma("unroll") for (int k = 0; k < 2; ++k) \
;         acc[ai][bj][m][n] = __builtin_amdgcn_mfma_f32_16x16x32_bf16(Bt[n][k], At[m][k], acc[ai][bj][m][n], 0, 0, 0); __builtin_amdgcn_s_setprio(0); } while (0)
; #define PG8_WAIT_V(n) asm volatile("s_waitcnt vmcnt(" #n ")" ::: "memory")
; #define PG8_WAIT_L(n) asm volatile("s_waitcnt lgkmcnt(" #n ")" ::: "memory")
; #define PG8_BAR __builtin_amdgcn_s_barrier()
; #define PG8_SCHED __builtin_amdgcn_sched_barrier(0)
; template <class Epi>
; __device__ __forceinline__ void gemm_phase(LAS unsigned char* lds, const Gemm g, const StaticOrder& S, const Epi& E) {
;     ...
;             PG8_WAIT_V(8); PG8_WAIT_L(0); PG8_BAR; PG8_MMA(1, 0, At, B0); PG8_MMA(1, 1, At, B1); PG8_BAR; PG8_SCHED;
;             PG8_LDB(B0, 1, 0); PG8_LDB(B1, 1, 1); PG8_SCHED; PG8_LDA(At, 1, 0); PG8_STAGE(PG8_SA(0, 1), a2 + hstep, voffA);
;             PG8_WAIT_V(8); PG8_WAIT_L(0); PG8_BAR; PG8_MMA(0, 0, At, B0); PG8_MMA(0, 1, At, B1); PG8_BAR; PG8_SCHED;
	s_waitcnt lgkmcnt(0)
	v_mfma_f32_16x16x32_bf16 v[60:63], v[146:149], v[194:197], v[60:63]
	v_mfma_f32_16x16x32_bf16 v[56:59], v[170:173], v[194:197], v[56:59]
	v_mfma_f32_16x16x32_bf16 v[44:47], v[146:149], v[202:205], v[44:47]
	v_mfma_f32_16x16x32_bf16 v[40:43], v[170:173], v[202:205], v[40:43]
	v_mfma_f32_16x16x32_bf16 v[28:31], v[146:149], v[226:229], v[28:31]
	v_mfma_f32_16x16x32_bf16 v[24:27], v[170:173], v[226:229], v[24:27]
	v_mfma_f32_16x16x32_bf16 v[12:15], v[146:149], v[234:237], v[12:15]
	v_mfma_f32_16x16x32_bf16 v[8:11], v[170:173], v[234:237], v[8:11]
	v_mfma_f32_16x16x32_bf16 v[60:63], v[150:153], v[198:201], v[60:63]
	v_mfma_f32_16x16x32_bf16 v[56:59], v[174:177], v[198:201], v[56:59]
	v_mfma_f32_16x16x32_bf16 v[44:47], v[150:153], v[206:209], v[44:47]
	v_mfma_f32_16x16x32_bf16 v[40:43], v[174:177], v[206:209], v[40:43]
	v_mfma_f32_16x16x32_bf16 v[28:31], v[150:153], v[230:233], v[28:31]
	v_mfma_f32_16x16x32_bf16 v[24:27], v[174:177], v[230:233], v[24:27]
	v_mfma_f32_16x16x32_bf16 v[12:15], v[150:153], v[238:241], v[12:15]
	v_mfma_f32_16x16x32_bf16 v[8:11], v[174:177], v[238:241], v[8:11]
	v_mfma_f32_16x16x32_bf16 v[52:55], v[178:181], v[194:197], v[52:55]
	v_mfma_f32_16x16x32_bf16 v[48:51], v[186:189], v[194:197], v[48:51]
	v_mfma_f32_16x16x32_bf16 v[36:39], v[178:181], v[202:205], v[36:39]
	v_mfma_f32_16x16x32_bf16 v[32:35], v[186:189], v[202:205], v[32:35]
	v_mfma_f32_16x16x32_bf16 v[20:23], v[178:181], v[226:229], v[20:23]
	v_mfma_f32_16x16x32_bf16 v[16:19], v[186:189], v[226:229], v[16:19]
	v_mfma_f32_16x16x32_bf16 v[4:7], v[178:181], v[234:237], v[4:7]
	v_mfma_f32_16x16x32_bf16 v[0:3], v[186:189], v[234:237], v[0:3]
	v_mfma_f32_16x16x32_bf16 v[52:55], v[182:185], v[198:201], v[52:55]
	v_mfma_f32_16x16x32_bf16 v[48:51], v[190:193], v[198:201], v[48:51]
	v_mfma_f32_16x16x32_bf16 v[36:39], v[182:185], v[206:209], v[36:39]
	v_mfma_f32_16x16x32_bf16 v[32:35], v[190:193], v[206:209], v[32:35]
	v_mfma_f32_16x16x32_bf16 v[20:23], v[182:185], v[230:233], v[20:23]
	v_mfma_f32_16x16x32_bf16 v[16:19], v[190:193], v[230:233], v[16:19]
	v_mfma_f32_16x16x32_bf16 v[4:7], v[182:185], v[238:241], v[4:7]
	v_mfma_f32_16x16x32_bf16 v[0:3], v[190:193], v[238:241], v[0:3]
	s_barrier
	v_or_b32_e32 v141, 0x18000, v162
	v_add_u32_e32 v144, 0x18400, v162
	ds_read_b128 v[146:149], v141
	ds_read_b128 v[150:153], v144
	v_add_u32_e32 v141, 0x18800, v162
	v_add_u32_e32 v144, 0x18c00, v162
	ds_read_b128 v[170:173], v141
	ds_read_b128 v[174:177], v144
	v_or_b32_e32 v141, 0x1c000, v162
	v_add_u32_e32 v144, 0x1c400, v162
	ds_read_b128 v[178:181], v141
	ds_read_b128 v[182:185], v144
	v_add_u32_e32 v141, 0x1c800, v162
	v_add_u32_e32 v144, 0x1cc00, v162
	ds_read_b128 v[186:189], v141
	ds_read_b128 v[190:193], v144
	s_add_u32 s10, s10, s20
	s_addc_u32 s11, s11, s21
	s_mov_b32 m0, s50
	v_lshl_add_u64 v[244:245], s[10:11], 0, v[128:129]
	ds_read_b128 v[194:197], v155 offset:32768
	ds_read_b128 v[198:201], v155 offset:33792
	ds_read_b128 v[202:205], v155 offset:34816
	ds_read_b128 v[206:209], v155 offset:35840
	ds_read_b128 v[226:229], v155 offset:36864
	ds_read_b128 v[230:233], v155 offset:37888
	ds_read_b128 v[234:237], v155 offset:38912
	ds_read_b128 v[238:241], v155 offset:39936
	global_load_lds_dwordx4 v[244:245], off
	v_lshl_add_u64 v[244:245], s[10:11], 0, v[130:131]
	s_mov_b32 m0, s51
	s_nop 0
	global_load_lds_dwordx4 v[244:245], off
	s_waitcnt vmcnt(8)
	s_waitcnt lgkmcnt(0)
	s_barrier
	s_waitcnt lgkmcnt(0)
	v_mfma_f32_16x16x32_bf16 v[120:123], v[146:149], v[194:197], v[120:123]
	v_mfma_f32_16x16x32_bf16 v[124:127], v[170:173], v[194:197], v[124:127]
	v_mfma_f32_16x16x32_bf16 v[108:111], v[146:149], v[202:205], v[108:111]
	v_mfma_f32_16x16x32_bf16 v[104:107], v[170:173], v[202:205], v[104:107]
	v_mfma_f32_16x16x32_bf16 v[92:95], v[146:149], v[226:229], v[92:95]
	v_mfma_f32_16x16x32_bf16 v[88:91], v[170:173], v[226:229], v[88:91]
	v_mfma_f32_16x16x32_bf16 v[76:79], v[146:149], v[234:237], v[76:79]
	v_mfma_f32_16x16x32_bf16 v[72:75], v[170:173], v[234:237], v[72:75]
	v_mfma_f32_16x16x32_bf16 v[120:123], v[150:153], v[198:201], v[120:123]
	v_mfma_f32_16x16x32_bf16 v[124:127], v[174:177], v[198:201], v[124:127]
	v_mfma_f32_16x16x32_bf16 v[108:111], v[150:153], v[206:209], v[108:111]
	v_mfma_f32_16x16x32_bf16 v[104:107], v[174:177], v[206:209], v[104:107]
	v_mfma_f32_16x16x32_bf16 v[92:95], v[150:153], v[230:233], v[92:95]
	v_mfma_f32_16x16x32_bf16 v[88:91], v[174:177], v[230:233], v[88:91]
	v_mfma_f32_16x16x32_bf16 v[76:79], v[150:153], v[238:241], v[76:79]
	v_mfma_f32_16x16x32_bf16 v[72:75], v[174:177], v[238:241], v[72:75]
	v_mfma_f32_16x16x32_bf16 v[116:119], v[178:181], v[194:197], v[116:119]
	v_mfma_f32_16x16x32_bf16 v[112:115], v[186:189], v[194:197], v[112:115]
	v_mfma_f32_16x16x32_bf16 v[100:103], v[178:181], v[202:205], v[100:103]
	v_mfma_f32_16x16x32_bf16 v[96:99], v[186:189], v[202:205], v[96:99]
	v_mfma_f32_16x16x32_bf16 v[84:87], v[178:181], v[226:229], v[84:87]
	v_mfma_f32_16x16x32_bf16 v[80:83], v[186:189], v[226:229], v[80:83]
	v_mfma_f32_16x16x32_bf16 v[68:71], v[178:181], v[234:237], v[68:71]
	v_mfma_f32_16x16x32_bf16 v[64:67], v[186:189], v[234:237], v[64:67]
	v_mfma_f32_16x16x32_bf16 v[116:119], v[182:185], v[198:201], v[116:119]
	v_mfma_f32_16x16x32_bf16 v[112:115], v[190:193], v[198:201], v[112:115]
	v_mfma_f32_16x16x32_bf16 v[100:103], v[182:185], v[206:209], v[100:103]
	v_mfma_f32_16x16x32_bf16 v[96:99], v[190:193], v[206:209], v[96:99]
	v_mfma_f32_16x16x32_bf16 v[84:87], v[182:185], v[230:233], v[84:87]
	v_mfma_f32_16x16x32_bf16 v[80:83], v[190:193], v[230:233], v[80:83]
	v_mfma_f32_16x16x32_bf16 v[68:71], v[182:185], v[238:241], v[68:71]
	v_mfma_f32_16x16x32_bf16 v[64:67], v[190:193], v[238:241], v[64:67]
	s_barrier
; #define PG8_STAGE(bufoff, gbase, voff) do { _Pragma("unroll") for (int _i = 0; _i < 2; ++_i) \
;         __builtin_amdgcn_global_load_lds((const unsigned*)((const char*)(gbase) + (voff)[_i]), (LAS unsigned*)(lds + (bufoff) + ldsw + _i * 8192), 16, 0, 0); } while (0)
; #define PG8_LDA(dst, b, h) do { _Pragma("unroll") for (int m = 0; m < 4; ++m) _Pragma("unroll") for (int k = 0; k < 2; ++k) dst[m][k] = *(const LAS bf16x8*)(lds + PG8_SA(b, h) + aoff + m * 2048 + k * 1024); } while (0)
; #define PG8_MMA(ai, bj, At, Bt) do { __builtin_amdgcn_s_setprio(1); _Pragma("unroll") for (int m = 0; m < 4; ++m) _Pragma("unroll") for (int n = 0; n < 2; ++n) _Pragma("unroll") for (int k = 0; k < 2; ++k) \
;         acc[ai][bj][m][n] = __builtin_amdgcn_mfma_f32_16x16x32_bf16(Bt[n][k], At[m][k], acc[ai][bj][m][n], 0, 0, 0); __builtin_amdgcn_s_setprio(0); } while (0)
; #define PG8_WAIT_V(n) asm volatile("s_waitcnt vmcnt(" #n ")" ::: "memory")
; #define PG8_WAIT_L(n) asm volatile("s_waitcnt lgkmcnt(" #n ")" ::: "memory")
; #define PG8_BAR __builtin_amdgcn_s_barrier()
; #define PG8_SCHED __builtin_amdgcn_sched_barrier(0)
; template <class Epi>
; __device__ __forceinline__ void gemm_phase(LAS unsigned char* lds, const Gemm g, const StaticOrder& S, const Epi& E) {
;     ...
;             PG8_LDA(At, 1, 1); PG8_STAGE(PG8_SB(1, 0), b3, voffB); PG8_STAGE(PG8_SB(1, 1), b3 + hstep, voffB); PG8_STAGE(PG8_SA(1, 0), a3, voffA);
;             PG8_WAIT_V(8); PG8_WAIT_L(0); PG8_BAR; PG8_MMA(1, 0, At, B0); PG8_MMA(1, 1, At, B1); PG8_BAR; PG8_SCHED;
;         }
	s_mov_b32 m0, s52
	v_lshl_add_u64 v[142:143], v[142:143], 0, s[82:83]
	ds_read_b128 v[194:197], v155 offset:49152
	ds_read_b128 v[198:201], v155 offset:50176
	ds_read_b128 v[202:205], v155 offset:51200
	ds_read_b128 v[206:209], v155 offset:52224
	ds_read_b128 v[226:229], v155 offset:53248
	ds_read_b128 v[230:233], v155 offset:54272
	ds_read_b128 v[234:237], v155 offset:55296
	ds_read_b128 v[238:241], v155 offset:56320
	global_load_lds_dwordx4 v[142:143], off
	v_lshl_add_u64 v[142:143], v[210:211], 0, s[82:83]
	s_mov_b32 m0, s53
	s_nop 0
	global_load_lds_dwordx4 v[142:143], off
	v_lshl_add_u64 v[142:143], v[216:217], 0, s[82:83]
	s_mov_b32 m0, s58
	s_nop 0
	global_load_lds_dwordx4 v[142:143], off
	v_lshl_add_u64 v[142:143], v[218:219], 0, s[82:83]
	s_mov_b32 m0, s59
	s_nop 0
	global_load_lds_dwordx4 v[142:143], off
	v_lshl_add_u64 v[142:143], v[220:221], 0, s[82:83]
	s_mov_b32 m0, s54
	s_nop 0
	global_load_lds_dwordx4 v[142:143], off
	v_lshl_add_u64 v[142:143], v[242:243], 0, s[82:83]
	s_mov_b32 m0, s55
	s_nop 0
	global_load_lds_dwordx4 v[142:143], off
	s_waitcnt vmcnt(8)
	s_waitcnt lgkmcnt(0)
	s_barrier
	s_waitcnt lgkmcnt(0)
	v_mfma_f32_16x16x32_bf16 v[60:63], v[146:149], v[194:197], v[60:63]
	v_mfma_f32_16x16x32_bf16 v[56:59], v[170:173], v[194:197], v[56:59]
	v_mfma_f32_16x16x32_bf16 v[44:47], v[146:149], v[202:205], v[44:47]
	v_mfma_f32_16x16x32_bf16 v[40:43], v[170:173], v[202:205], v[40:43]
	v_mfma_f32_16x16x32_bf16 v[28:31], v[146:149], v[226:229], v[28:31]
	v_mfma_f32_16x16x32_bf16 v[24:27], v[170:173], v[226:229], v[24:27]
	v_mfma_f32_16x16x32_bf16 v[12:15], v[146:149], v[234:237], v[12:15]
	v_mfma_f32_16x16x32_bf16 v[8:11], v[170:173], v[234:237], v[8:11]
	v_mfma_f32_16x16x32_bf16 v[60:63], v[150:153], v[198:201], v[60:63]
	v_mfma_f32_16x16x32_bf16 v[56:59], v[174:177], v[198:201], v[56:59]
	v_mfma_f32_16x16x32_bf16 v[44:47], v[150:153], v[206:209], v[44:47]
	v_mfma_f32_16x16x32_bf16 v[40:43], v[174:177], v[206:209], v[40:43]
	v_mfma_f32_16x16x32_bf16 v[28:31], v[150:153], v[230:233], v[28:31]
	v_mfma_f32_16x16x32_bf16 v[24:27], v[174:177], v[230:233], v[24:27]
	v_mfma_f32_16x16x32_bf16 v[12:15], v[150:153], v[238:241], v[12:15]
	v_mfma_f32_16x16x32_bf16 v[8:11], v[174:177], v[238:241], v[8:11]
	v_mfma_f32_16x16x32_bf16 v[52:55], v[178:181], v[194:197], v[52:55]
	v_mfma_f32_16x16x32_bf16 v[48:51], v[186:189], v[194:197], v[48:51]
	v_mfma_f32_16x16x32_bf16 v[36:39], v[178:181], v[202:205], v[36:39]
	v_mfma_f32_16x16x32_bf16 v[32:35], v[186:189], v[202:205], v[32:35]
	v_mfma_f32_16x16x32_bf16 v[20:23], v[178:181], v[226:229], v[20:23]
	v_mfma_f32_16x16x32_bf16 v[16:19], v[186:189], v[226:229], v[16:19]
	v_mfma_f32_16x16x32_bf16 v[4:7], v[178:181], v[234:237], v[4:7]
	v_mfma_f32_16x16x32_bf16 v[0:3], v[186:189], v[234:237], v[0:3]
	v_mfma_f32_16x16x32_bf16 v[52:55], v[182:185], v[198:201], v[52:55]
	v_mfma_f32_16x16x32_bf16 v[48:51], v[190:193], v[198:201], v[48:51]
	v_mfma_f32_16x16x32_bf16 v[36:39], v[182:185], v[206:209], v[36:39]
	v_mfma_f32_16x16x32_bf16 v[32:35], v[190:193], v[206:209], v[32:35]
	v_mfma_f32_16x16x32_bf16 v[20:23], v[182:185], v[230:233], v[20:23]
	v_mfma_f32_16x16x32_bf16 v[16:19], v[190:193], v[230:233], v[16:19]
	v_mfma_f32_16x16x32_bf16 v[4:7], v[182:185], v[238:241], v[4:7]
	v_mfma_f32_16x16x32_bf16 v[0:3], v[190:193], v[238:241], v[0:3]
	s_barrier
	s_add_u32 s2, s2, 0x100
	s_addc_u32 s3, s3, 0
	s_add_u32 s69, s69, 0x100
	s_addc_u32 s70, s70, 0
	s_cmp_ge_i32 s71, s61
	s_cbranch_scc1 .LBB0_986
